# X54: X53 plus three mixer latency edits re-tested together with the paired measurement: Mamba-2 pass-1 dt*A cumulative-sum reads issued up front, RG-LRU output-pass gate lines requested in one round t
# speedup vs baseline: 1.0045x; 1.0010x over previous
; __device__ __forceinline__ unsigned pkbf(float a, float b) { return pk2(a, b); }
; __device__ __forceinline__ void lru_load_w(const Args& a, int l, int wave, int lane, LruW& W) {
;     const int fr = lane & 15, g = lane >> 4; const float* wa = a.in[I_LWA] + ((size_t)l * 8 + wave) * 4096; const float* wx = a.in[I_LWX] + ((size_t)l * 8 + wave) * 4096;
; #pragma unroll
;     for (int nt = 0; nt < 4; ++nt)
; #pragma unroll
;         for (int ks = 0; ks < 2; ++ks) { unsigned pa[4], px[4];
; #pragma unroll
;             for (int e = 0; e < 4; ++e) { const int i0 = 32 * ks + 8 * g + 2 * e, j = 16 * nt + fr; pa[e] = pkbf(wa[i0 * 64 + j], wa[(i0 + 1) * 64 + j]); px[e] = pkbf(wx[i0 * 64 + j], wx[(i0 + 1) * 64 + j]); }
;             W.wa[nt][ks] = __builtin_bit_cast(bf16x8_t, (v4u){pa[0], pa[1], pa[2], pa[3]}); W.wx[nt][ks] = __builtin_bit_cast(bf16x8_t, (v4u){px[0], px[1], px[2], px[3]}); }
; }
.LBB0_488:
	v_readlane_b32 s2, v254, 15
	v_readlane_b32 s3, v254, 16
	s_andn2_b64 vcc, exec, s[2:3]
	v_readlane_b32 s2, v255, 18
	v_readlane_b32 s3, v255, 19
	s_mov_b32 s3, s25
	v_writelane_b32 v255, s2, 18
	v_and_b32_e32 v1, 15, v210
	s_nop 0
	v_writelane_b32 v255, s3, 19
	s_cbranch_vccnz .LBB0_797
	v_readlane_b32 s2, v255, 25
	v_readlane_b32 s4, v255, 18
	v_readlane_b32 s3, v255, 26
	s_mov_b32 s8, s2
	s_ashr_i32 s9, s2, 31
	v_readlane_b32 s5, v255, 19
	s_lshl_b64 s[2:3], s[4:5], 15
	s_lshl_b64 s[22:23], s[8:9], 12
	s_add_u32 s2, s22, s2
	s_addc_u32 s3, s23, s3
	s_lshl_b64 s[2:3], s[2:3], 2
	s_add_u32 s22, s86, s2
	s_addc_u32 s23, s87, s3
	s_add_u32 s36, s90, s2
	v_lshlrev_b32_e32 v2, 5, v211
	s_movk_i32 s2, 0x600
	v_and_or_b32 v2, v2, s2, v1
	v_lshlrev_b32_e32 v2, 2, v2
	s_addc_u32 s37, s91, s3
	s_add_u32 s44, s0, 0x3ab00000
	s_addc_u32 s45, s1, 0
	s_mov_b32 s6, s8
	s_add_u32 s46, s0, 0x3ac00000
	v_writelane_b32 v255, s6, 25
	s_addc_u32 s47, s1, 0
	s_lshl_b64 s[2:3], s[4:5], 13
	v_writelane_b32 v255, s7, 26
	s_add_u32 s48, s82, s2
	s_addc_u32 s49, s83, s3
	v_readlane_b32 s2, v255, 6
	s_lshl_b32 s24, s4, 9
	s_mov_b32 s52, s2
	v_readlane_b32 s3, v255, 7
	s_waitcnt lgkmcnt(0)
	v_add_u32_e32 v3, 0x1000, v2
	v_add_u32_e32 v4, 0x2000, v2
	global_load_dword v6, v4, s[36:37] offset:192
	global_load_dword v70, v4, s[36:37] offset:448
	global_load_dword v7, v4, s[36:37] offset:704
	global_load_dword v71, v4, s[36:37] offset:960
	global_load_dword v8, v4, s[36:37] offset:1216
	global_load_dword v72, v4, s[36:37] offset:1472
	global_load_dword v9, v4, s[36:37] offset:1728
	global_load_dword v73, v4, s[36:37] offset:1984
	global_load_dword v10, v4, s[22:23] offset:192
	global_load_dword v74, v4, s[22:23] offset:448
	global_load_dword v11, v4, s[22:23] offset:704
	global_load_dword v75, v4, s[22:23] offset:960
	global_load_dword v12, v4, s[22:23] offset:1216
	global_load_dword v76, v4, s[22:23] offset:1472
	global_load_dword v13, v4, s[22:23] offset:1728
	global_load_dword v77, v4, s[22:23] offset:1984
	global_load_dword v14, v2, s[36:37] offset:192
	global_load_dword v78, v2, s[36:37] offset:448
	global_load_dword v15, v2, s[36:37] offset:704
	global_load_dword v79, v2, s[36:37] offset:960
	global_load_dword v16, v2, s[36:37] offset:1216
	global_load_dword v80, v2, s[36:37] offset:1472
	global_load_dword v17, v2, s[36:37] offset:1728
	global_load_dword v81, v2, s[36:37] offset:1984
	global_load_dword v18, v2, s[22:23] offset:192
	global_load_dword v82, v2, s[22:23] offset:448
	global_load_dword v19, v2, s[22:23] offset:704
	global_load_dword v83, v2, s[22:23] offset:960
	global_load_dword v20, v2, s[22:23] offset:1216
	global_load_dword v84, v2, s[22:23] offset:1472
	global_load_dword v21, v2, s[22:23] offset:1728
	global_load_dword v85, v2, s[22:23] offset:1984
	global_load_dword v22, v4, s[36:37] offset:128
	global_load_dword v86, v4, s[36:37] offset:384
	global_load_dword v23, v4, s[36:37] offset:640
	global_load_dword v87, v4, s[36:37] offset:896
	global_load_dword v24, v4, s[36:37] offset:1152
	global_load_dword v88, v4, s[36:37] offset:1408
	global_load_dword v25, v4, s[36:37] offset:1664
	global_load_dword v89, v4, s[36:37] offset:1920
	global_load_dword v26, v4, s[22:23] offset:128
	global_load_dword v90, v4, s[22:23] offset:384
	global_load_dword v27, v4, s[22:23] offset:640
	global_load_dword v91, v4, s[22:23] offset:896
	global_load_dword v28, v4, s[22:23] offset:1152
	global_load_dword v92, v4, s[22:23] offset:1408
	global_load_dword v29, v4, s[22:23] offset:1664
	global_load_dword v93, v4, s[22:23] offset:1920
	global_load_dword v30, v2, s[36:37] offset:128
	global_load_dword v94, v2, s[36:37] offset:384
	global_load_dword v31, v2, s[36:37] offset:640
	global_load_dword v95, v2, s[36:37] offset:896
	global_load_dword v32, v2, s[36:37] offset:1152
	global_load_dword v96, v2, s[36:37] offset:1408
	global_load_dword v33, v2, s[36:37] offset:1664
	global_load_dword v97, v2, s[36:37] offset:1920
	global_load_dword v34, v2, s[22:23] offset:128
	global_load_dword v98, v2, s[22:23] offset:384
	global_load_dword v35, v2, s[22:23] offset:640
	global_load_dword v99, v2, s[22:23] offset:896
	global_load_dword v36, v2, s[22:23] offset:1152
	global_load_dword v100, v2, s[22:23] offset:1408
	global_load_dword v37, v2, s[22:23] offset:1664
	global_load_dword v101, v2, s[22:23] offset:1920
	global_load_dword v38, v4, s[36:37] offset:64
	global_load_dword v102, v4, s[36:37] offset:320
	global_load_dword v39, v4, s[36:37] offset:576
	global_load_dword v103, v4, s[36:37] offset:832
	global_load_dword v40, v4, s[36:37] offset:1088
	global_load_dword v104, v4, s[36:37] offset:1344
	global_load_dword v41, v4, s[36:37] offset:1600
	global_load_dword v105, v4, s[36:37] offset:1856
	global_load_dword v42, v4, s[22:23] offset:64
; __device__ __forceinline__ unsigned pkbf(float a, float b) { return pk2(a, b); }
; __device__ __forceinline__ void lru_load_w(const Args& a, int l, int wave, int lane, LruW& W) {
;     ...
;         for (int ks = 0; ks < 2; ++ks) { unsigned pa[4], px[4];
; #pragma unroll
;             for (int e = 0; e < 4; ++e) { const int i0 = 32 * ks + 8 * g + 2 * e, j = 16 * nt + fr; pa[e] = pkbf(wa[i0 * 64 + j], wa[(i0 + 1) * 64 + j]); px[e] = pkbf(wx[i0 * 64 + j], wx[(i0 + 1) * 64 + j]); }
;             W.wa[nt][ks] = __builtin_bit_cast(bf16x8_t, (v4u){pa[0], pa[1], pa[2], pa[3]}); W.wx[nt][ks] = __builtin_bit_cast(bf16x8_t, (v4u){px[0], px[1], px[2], px[3]}); }
	global_load_dword v106, v4, s[22:23] offset:320
	global_load_dword v43, v4, s[22:23] offset:576
	global_load_dword v107, v4, s[22:23] offset:832
	global_load_dword v44, v4, s[22:23] offset:1088
	global_load_dword v108, v4, s[22:23] offset:1344
	global_load_dword v45, v4, s[22:23] offset:1600
	global_load_dword v109, v4, s[22:23] offset:1856
	global_load_dword v46, v2, s[36:37] offset:64
	global_load_dword v110, v2, s[36:37] offset:320
	global_load_dword v47, v2, s[36:37] offset:576
	global_load_dword v111, v2, s[36:37] offset:832
	global_load_dword v48, v2, s[36:37] offset:1088
	global_load_dword v112, v2, s[36:37] offset:1344
	global_load_dword v49, v2, s[36:37] offset:1600
	global_load_dword v113, v2, s[36:37] offset:1856
	global_load_dword v50, v2, s[22:23] offset:64
	global_load_dword v114, v2, s[22:23] offset:320
	global_load_dword v51, v2, s[22:23] offset:576
	global_load_dword v115, v2, s[22:23] offset:832
	global_load_dword v52, v2, s[22:23] offset:1088
	global_load_dword v116, v2, s[22:23] offset:1344
	global_load_dword v53, v2, s[22:23] offset:1600
	global_load_dword v117, v2, s[22:23] offset:1856
	global_load_dword v54, v4, s[36:37]
	global_load_dword v118, v4, s[36:37] offset:256
	global_load_dword v55, v4, s[36:37] offset:512
	global_load_dword v119, v4, s[36:37] offset:768
	global_load_dword v56, v4, s[36:37] offset:1024
	global_load_dword v120, v4, s[36:37] offset:1280
	global_load_dword v57, v4, s[36:37] offset:1536
	global_load_dword v121, v4, s[36:37] offset:1792
	global_load_dword v58, v4, s[22:23]
	global_load_dword v122, v4, s[22:23] offset:256
	global_load_dword v59, v4, s[22:23] offset:512
	global_load_dword v123, v4, s[22:23] offset:768
	global_load_dword v60, v4, s[22:23] offset:1024
	global_load_dword v124, v4, s[22:23] offset:1280
	global_load_dword v61, v4, s[22:23] offset:1536
	global_load_dword v125, v4, s[22:23] offset:1792
	global_load_dword v62, v2, s[36:37]
	global_load_dword v126, v2, s[36:37] offset:256
	global_load_dword v63, v2, s[36:37] offset:512
	global_load_dword v127, v2, s[36:37] offset:768
	global_load_dword v64, v2, s[36:37] offset:1024
	global_load_dword v128, v2, s[36:37] offset:1280
	global_load_dword v65, v2, s[36:37] offset:1536
	global_load_dword v129, v2, s[36:37] offset:1792
	global_load_dword v66, v2, s[22:23]
	global_load_dword v130, v2, s[22:23] offset:256
	global_load_dword v67, v2, s[22:23] offset:512
	global_load_dword v131, v2, s[22:23] offset:768
	global_load_dword v68, v2, s[22:23] offset:1024
	global_load_dword v132, v2, s[22:23] offset:1280
	global_load_dword v69, v2, s[22:23] offset:1536
	global_load_dword v133, v2, s[22:23] offset:1792
	s_waitcnt vmcnt(0)
	v_cvt_pk_bf16_f32 v6, v6, v70
	v_cvt_pk_bf16_f32 v7, v7, v71
	v_cvt_pk_bf16_f32 v8, v8, v72
	v_cvt_pk_bf16_f32 v9, v9, v73
	v_cvt_pk_bf16_f32 v10, v10, v74
	v_cvt_pk_bf16_f32 v11, v11, v75
	v_cvt_pk_bf16_f32 v12, v12, v76
	v_cvt_pk_bf16_f32 v13, v13, v77
	v_cvt_pk_bf16_f32 v14, v14, v78
	v_cvt_pk_bf16_f32 v15, v15, v79
	v_cvt_pk_bf16_f32 v16, v16, v80
	v_cvt_pk_bf16_f32 v17, v17, v81
	v_cvt_pk_bf16_f32 v18, v18, v82
	v_cvt_pk_bf16_f32 v19, v19, v83
	v_cvt_pk_bf16_f32 v20, v20, v84
	v_cvt_pk_bf16_f32 v21, v21, v85
	v_cvt_pk_bf16_f32 v22, v22, v86
	v_cvt_pk_bf16_f32 v23, v23, v87
	v_cvt_pk_bf16_f32 v24, v24, v88
	v_cvt_pk_bf16_f32 v25, v25, v89
	v_cvt_pk_bf16_f32 v26, v26, v90
	v_cvt_pk_bf16_f32 v27, v27, v91
	v_cvt_pk_bf16_f32 v28, v28, v92
	v_cvt_pk_bf16_f32 v29, v29, v93
	v_cvt_pk_bf16_f32 v30, v30, v94
	v_cvt_pk_bf16_f32 v31, v31, v95
	v_cvt_pk_bf16_f32 v32, v32, v96
	v_cvt_pk_bf16_f32 v33, v33, v97
	v_cvt_pk_bf16_f32 v34, v34, v98
	v_cvt_pk_bf16_f32 v35, v35, v99
	v_cvt_pk_bf16_f32 v36, v36, v100
	v_cvt_pk_bf16_f32 v37, v37, v101
	v_cvt_pk_bf16_f32 v38, v38, v102
	v_cvt_pk_bf16_f32 v39, v39, v103
	v_cvt_pk_bf16_f32 v40, v40, v104
	v_cvt_pk_bf16_f32 v41, v41, v105
	v_cvt_pk_bf16_f32 v42, v42, v106
	v_cvt_pk_bf16_f32 v43, v43, v107
	v_cvt_pk_bf16_f32 v44, v44, v108
	v_cvt_pk_bf16_f32 v45, v45, v109
	v_cvt_pk_bf16_f32 v46, v46, v110
	v_cvt_pk_bf16_f32 v47, v47, v111
	v_cvt_pk_bf16_f32 v48, v48, v112
	v_cvt_pk_bf16_f32 v49, v49, v113
	v_cvt_pk_bf16_f32 v50, v50, v114
	v_cvt_pk_bf16_f32 v51, v51, v115
	v_cvt_pk_bf16_f32 v52, v52, v116
	v_cvt_pk_bf16_f32 v53, v53, v117
	v_cvt_pk_bf16_f32 v54, v54, v118
	v_cvt_pk_bf16_f32 v55, v55, v119
	v_cvt_pk_bf16_f32 v56, v56, v120
	v_cvt_pk_bf16_f32 v57, v57, v121
	v_cvt_pk_bf16_f32 v58, v58, v122
	v_cvt_pk_bf16_f32 v59, v59, v123
	v_cvt_pk_bf16_f32 v60, v60, v124
	v_cvt_pk_bf16_f32 v61, v61, v125
	v_cvt_pk_bf16_f32 v62, v62, v126
	v_cvt_pk_bf16_f32 v63, v63, v127
	v_cvt_pk_bf16_f32 v64, v64, v128
	v_cvt_pk_bf16_f32 v65, v65, v129
	v_cvt_pk_bf16_f32 v66, v66, v130
	v_cvt_pk_bf16_f32 v67, v67, v131
	v_cvt_pk_bf16_f32 v68, v68, v132
	v_cvt_pk_bf16_f32 v69, v69, v133
	s_branch .LBB0_491

; __device__ __forceinline__ float softplusf_(float v) { return v > 20.f ? v : log1pf(__expf(v)); }
; __device__ __forceinline__ void sd_p1_unit(const Args& a, unsigned char* ws, int l, const rs_t* rowss, int unit, LAS unsigned char* lds, int tid_in) {
;     ...
;     { const int t = tid >> 3, h = tid & 7; float s = 0.f;
; #pragma unroll
;       for (int w = 0; w < 8; ++w) s += part[(w * 64 + t) * 8 + h];
;       const float r = 1.0f / sqrtf((float)rowss[row0 + t] * (RS_INV / DM) + NORM_EPS);
;       const float dt = softplusf_(s * r + a.in[I_SDTB][l * 8 + h]); dtl[t * 8 + h] = dt; DTV[(row0 + t) * 8 + h] = dt; }
;     __syncthreads();
;     if (tid < 8) { const float An = -__expf(a.in[I_SALOG][l * 8 + tid]); float run = 0.f; for (int t = 0; t < 64; ++t) { run += dtl[t * 8 + tid] * An; acs[t * 8 + tid] = run; }
;         CDEC[(size_t)(b * 256 + chunk) * 8 + tid] = __expf(run); }
.LBB0_781:
	s_or_b64 exec, exec, s[22:23]
	v_lshlrev_b64 v[8:9], 5, v[8:9]
	v_lshl_add_u64 v[8:9], s[44:45], 0, v[8:9]
	v_mov_b32_e32 v7, v5
	v_lshl_add_u32 v4, v34, 2, 0
	v_lshl_add_u64 v[6:7], v[8:9], 0, v[6:7]
	v_cmp_lt_i32_e32 vcc, 7, v34
	ds_write_b32 v4, v10
	global_store_dword v[6:7], v10, off
	s_waitcnt lgkmcnt(0)
	s_barrier
	s_and_saveexec_b64 s[22:23], vcc
	s_xor_b64 s[22:23], exec, s[22:23]
	v_mov_b32_e32 v35, v5
	v_mov_b64_e32 v[6:7], v[34:35]
	s_or_saveexec_b64 s[22:23], s[22:23]
	v_ashrrev_i32_e32 v35, 31, v34
	s_xor_b64 exec, exec, s[22:23]
	s_cbranch_execz .LBB0_785
	v_add_u32_e32 v6, s59, v34
	v_readlane_b32 s4, v252, 21
	v_ashrrev_i32_e32 v7, 31, v6
	v_readlane_b32 s16, v252, 33
	v_readlane_b32 s17, v252, 34
	v_add_u32_e32 v10, 0x800, v4
	s_ashr_i32 s55, s54, 31
	v_lshl_add_u64 v[6:7], v[6:7], 2, s[16:17]
	global_load_dword v6, v[6:7], off
	s_lshl_b64 s[34:35], s[54:55], 5
	s_add_u32 s34, s24, s34
	s_addc_u32 s35, s58, s35
	v_readlane_b32 s5, v252, 22
	v_readlane_b32 s6, v252, 23
	v_readlane_b32 s7, v252, 24
	v_readlane_b32 s8, v252, 25
	v_readlane_b32 s9, v252, 26
	v_readlane_b32 s10, v252, 27
	v_readlane_b32 s11, v252, 28
	v_readlane_b32 s12, v252, 29
	v_readlane_b32 s13, v252, 30
	v_readlane_b32 s14, v252, 31
	v_readlane_b32 s15, v252, 32
	v_readlane_b32 s18, v252, 35
	v_readlane_b32 s19, v252, 36
	s_waitcnt vmcnt(0)
	v_mul_f32_e32 v6, 0x3fb8aa3b, v6
	v_exp_f32_e32 v8, v6
	ds_read2_b32 v[64:65], v4 offset1:8
	ds_read2_b32 v[66:67], v4 offset0:16 offset1:24
	ds_read2_b32 v[68:69], v4 offset0:32 offset1:40
	ds_read2_b32 v[70:71], v4 offset0:48 offset1:56
	ds_read2_b32 v[72:73], v4 offset0:64 offset1:72
	ds_read2_b32 v[74:75], v4 offset0:80 offset1:88
	ds_read2_b32 v[76:77], v4 offset0:96 offset1:104
	ds_read2_b32 v[78:79], v4 offset0:112 offset1:120
	ds_read2_b32 v[80:81], v4 offset0:128 offset1:136
	ds_read2_b32 v[82:83], v4 offset0:144 offset1:152
	ds_read2_b32 v[84:85], v4 offset0:160 offset1:168
	ds_read2_b32 v[86:87], v4 offset0:176 offset1:184
	ds_read2_b32 v[88:89], v4 offset0:192 offset1:200
	ds_read2_b32 v[90:91], v4 offset0:208 offset1:216
	ds_read2_b32 v[92:93], v4 offset0:224 offset1:232
	ds_read2_b32 v[94:95], v4 offset0:240 offset1:248
	v_add_u32_e32 v10, 0x400, v4
	ds_read2_b32 v[96:97], v10 offset1:8
	ds_read2_b32 v[98:99], v10 offset0:16 offset1:24
	ds_read2_b32 v[100:101], v10 offset0:32 offset1:40
	ds_read2_b32 v[102:103], v10 offset0:48 offset1:56
	ds_read2_b32 v[104:105], v10 offset0:64 offset1:72
	ds_read2_b32 v[106:107], v10 offset0:80 offset1:88
	ds_read2_b32 v[108:109], v10 offset0:96 offset1:104
	ds_read2_b32 v[110:111], v10 offset0:112 offset1:120
	ds_read2_b32 v[112:113], v10 offset0:128 offset1:136
	ds_read2_b32 v[114:115], v10 offset0:144 offset1:152
	ds_read2_b32 v[116:117], v10 offset0:160 offset1:168
	ds_read2_b32 v[118:119], v10 offset0:176 offset1:184
	ds_read2_b32 v[120:121], v10 offset0:192 offset1:200
	ds_read2_b32 v[122:123], v10 offset0:208 offset1:216
	ds_read2_b32 v[124:125], v10 offset0:224 offset1:232
	ds_read2_b32 v[126:127], v10 offset0:240 offset1:248
	v_add_u32_e32 v11, 0x800, v4
	v_add_u32_e32 v4, 0xc00, v4
	s_waitcnt lgkmcnt(0)
	v_fma_f32 v64, -v64, v8, 0
	v_fma_f32 v65, -v8, v65, v64
	ds_write2_b32 v11, v64, v65 offset1:8
	v_fma_f32 v66, -v8, v66, v65
	v_fma_f32 v67, -v8, v67, v66
	ds_write2_b32 v11, v66, v67 offset0:16 offset1:24
	v_fma_f32 v68, -v8, v68, v67
	v_fma_f32 v69, -v8, v69, v68
	ds_write2_b32 v11, v68, v69 offset0:32 offset1:40
	v_fma_f32 v70, -v8, v70, v69
	v_fma_f32 v71, -v8, v71, v70
	ds_write2_b32 v11, v70, v71 offset0:48 offset1:56
	v_fma_f32 v72, -v8, v72, v71
	v_fma_f32 v73, -v8, v73, v72
	ds_write2_b32 v11, v72, v73 offset0:64 offset1:72
	v_fma_f32 v74, -v8, v74, v73
	v_fma_f32 v75, -v8, v75, v74
	ds_write2_b32 v11, v74, v75 offset0:80 offset1:88
	v_fma_f32 v76, -v8, v76, v75
	v_fma_f32 v77, -v8, v77, v76
	ds_write2_b32 v11, v76, v77 offset0:96 offset1:104
	v_fma_f32 v78, -v8, v78, v77
	v_fma_f32 v79, -v8, v79, v78
	ds_write2_b32 v11, v78, v79 offset0:112 offset1:120
	v_fma_f32 v80, -v8, v80, v79
	v_fma_f32 v81, -v8, v81, v80
	ds_write2_b32 v11, v80, v81 offset0:128 offset1:136
	v_fma_f32 v82, -v8, v82, v81
	v_fma_f32 v83, -v8, v83, v82
	ds_write2_b32 v11, v82, v83 offset0:144 offset1:152
	v_fma_f32 v84, -v8, v84, v83
	v_fma_f32 v85, -v8, v85, v84
	ds_write2_b32 v11, v84, v85 offset0:160 offset1:168
	v_fma_f32 v86, -v8, v86, v85
	v_fma_f32 v87, -v8, v87, v86
	ds_write2_b32 v11, v86, v87 offset0:176 offset1:184
	v_fma_f32 v88, -v8, v88, v87
	v_fma_f32 v89, -v8, v89, v88
	ds_write2_b32 v11, v88, v89 offset0:192 offset1:200
	v_fma_f32 v90, -v8, v90, v89
	v_fma_f32 v91, -v8, v91, v90
	ds_write2_b32 v11, v90, v91 offset0:208 offset1:216
	v_fma_f32 v92, -v8, v92, v91
	v_fma_f32 v93, -v8, v93, v92
	ds_write2_b32 v11, v92, v93 offset0:224 offset1:232
	v_fma_f32 v94, -v8, v94, v93
	v_fma_f32 v95, -v8, v95, v94
	ds_write2_b32 v11, v94, v95 offset0:240 offset1:248
	v_fma_f32 v96, -v8, v96, v95
	v_fma_f32 v97, -v8, v97, v96
	ds_write2_b32 v4, v96, v97 offset1:8
	v_fma_f32 v98, -v8, v98, v97
	v_fma_f32 v99, -v8, v99, v98
	ds_write2_b32 v4, v98, v99 offset0:16 offset1:24
	v_fma_f32 v100, -v8, v100, v99
	v_fma_f32 v101, -v8, v101, v100
	ds_write2_b32 v4, v100, v101 offset0:32 offset1:40
	v_fma_f32 v102, -v8, v102, v101
	v_fma_f32 v103, -v8, v103, v102
	ds_write2_b32 v4, v102, v103 offset0:48 offset1:56
	v_fma_f32 v104, -v8, v104, v103
	v_fma_f32 v105, -v8, v105, v104
	ds_write2_b32 v4, v104, v105 offset0:64 offset1:72
	v_fma_f32 v106, -v8, v106, v105
	v_fma_f32 v107, -v8, v107, v106
	ds_write2_b32 v4, v106, v107 offset0:80 offset1:88
	v_fma_f32 v108, -v8, v108, v107
	v_fma_f32 v109, -v8, v109, v108
	ds_write2_b32 v4, v108, v109 offset0:96 offset1:104
	v_fma_f32 v110, -v8, v110, v109
	v_fma_f32 v111, -v8, v111, v110
	ds_write2_b32 v4, v110, v111 offset0:112 offset1:120
	v_fma_f32 v112, -v8, v112, v111
	v_fma_f32 v113, -v8, v113, v112
	ds_write2_b32 v4, v112, v113 offset0:128 offset1:136
	v_fma_f32 v114, -v8, v114, v113
	v_fma_f32 v115, -v8, v115, v114
	ds_write2_b32 v4, v114, v115 offset0:144 offset1:152
	v_fma_f32 v116, -v8, v116, v115
	v_fma_f32 v117, -v8, v117, v116
	ds_write2_b32 v4, v116, v117 offset0:160 offset1:168
	v_fma_f32 v118, -v8, v118, v117
	v_fma_f32 v119, -v8, v119, v118
	ds_write2_b32 v4, v118, v119 offset0:176 offset1:184
	v_fma_f32 v120, -v8, v120, v119
	v_fma_f32 v121, -v8, v121, v120
	ds_write2_b32 v4, v120, v121 offset0:192 offset1:200
	v_fma_f32 v122, -v8, v122, v121
	v_fma_f32 v123, -v8, v123, v122
	ds_write2_b32 v4, v122, v123 offset0:208 offset1:216
	v_fma_f32 v124, -v8, v124, v123
	v_fma_f32 v125, -v8, v125, v124
	ds_write2_b32 v4, v124, v125 offset0:224 offset1:232
	v_fma_f32 v126, -v8, v126, v125
	v_fma_f32 v127, -v8, v127, v126
	ds_write2_b32 v4, v126, v127 offset0:240 offset1:248
	v_mov_b32_e32 v6, v126
	v_mov_b32_e32 v7, v127
	v_mul_f32_e32 v4, 0x3fb8aa3b, v7
	v_exp_f32_e32 v4, v4
	v_lshl_add_u64 v[6:7], v[34:35], 2, s[34:35]
	global_store_dword v[6:7], v4, off
	v_mov_b64_e32 v[6:7], v[34:35]

; #define LAS __attribute__((address_space(3)))
; __device__ __forceinline__ float sigmoidf_(float v) { return __builtin_amdgcn_rcpf(1.0f + __builtin_amdgcn_exp2f(v * -1.4426950408889634f)); }
; template <bool FINAL> __device__ __forceinline__ void lru_unit(const Args& a, unsigned char* ws, int l, int unit, const LruW& W, LAS unsigned char* lds, int tid_in) {
;     ...
;         float av[4][4], bv[4][4]; const float carry0 = FINAL ? LRC[((size_t)b * 256 + chunk) * 512 + c] : 0.f;
; #pragma unroll
;         for (int mt = 0; mt < 4; ++mt) { pg8::f32x4 ra = {0.f, 0.f, 0.f, 0.f}, ri = {0.f, 0.f, 0.f, 0.f};
; #pragma unroll
;             for (int ks = 0; ks < 2; ++ks) { const bf16x8_t af = *(const LAS bf16x8_t*)(Xrm + (16 * mt + fr) * LR_RS + wave * 64 + 32 * ks + 8 * g);
;                 ra = __builtin_amdgcn_mfma_f32_16x16x32_bf16(af, W.wa[nt][ks], ra, 0, 0, 0); ri = __builtin_amdgcn_mfma_f32_16x16x32_bf16(af, W.wx[nt][ks], ri, 0, 0, 0); }
; #pragma unroll
;             for (int r = 0; r < 4; ++r) { const float rg = sigmoidf_(ra[r] + ba), ig = sigmoidf_(ri[r] + bx), la = -8.0f * rg * spn, xc = bf2f(Xrm[(16 * mt + 4 * g + r) * LR_RS + c]);
;                 const float x2 = 2.0f * la, em = (x2 > -0.25f) ? -x2 * (1.0f + x2 * (0.5f + x2 * (0.16666667f + x2 * (0.041666668f + x2 * 0.0083333338f)))) : 1.0f - __expf(x2);
;                 av[mt][r] = __expf(la); bv[mt][r] = __builtin_amdgcn_sqrtf(fmaxf(em, 0.f)) * (ig * xc); } }
.LBB0_1306:
	s_or_b64 exec, exec, s[36:37]
	v_bfe_u32 v91, v2, 4, 2
	v_and_b32_e32 v3, 0xffffffc0, v2
	v_lshlrev_b32_e32 v70, 1, v3
	v_lshlrev_b32_e32 v4, 4, v91
	v_and_b32_e32 v1, 15, v2
	s_lshl_b64 s[22:23], s[22:23], 19
	v_add3_u32 v78, 0, v70, v4
	s_movk_i32 s3, 0x410
	v_mad_u32_u24 v74, v1, s3, v78
	s_add_u32 s3, s48, s22
	s_addc_u32 s4, s49, s23
	s_lshl_b32 s2, s2, 11
	s_add_u32 s46, s3, s2
	s_addc_u32 s47, s4, 0
	v_ashrrev_i32_e32 v97, 31, v96
	v_lshl_add_u64 v[122:123], v[96:97], 2, s[46:47]
	global_load_dword v101, v[122:123], off
	ds_read_b128 v[70:73], v74
	ds_read_b128 v[80:83], v74 offset:64
	s_waitcnt lgkmcnt(1)
	v_mfma_f32_16x16x32_bf16 v[74:77], v[70:73], v[66:69], 0
	v_lshl_add_u32 v168, v96, 1, 0
	s_movk_i32 s2, 0x1040
	v_mad_u32_u24 v79, v91, s2, v168
	s_waitcnt lgkmcnt(0)
	v_mfma_f32_16x16x32_bf16 v[74:77], v[80:83], v[58:61], v[74:77]
	ds_read_u16 v92, v79
	v_mfma_f32_16x16x32_bf16 v[70:73], v[70:73], v[62:65], 0
	v_mfma_f32_16x16x32_bf16 v[70:73], v[80:83], v[54:57], v[70:73]
	s_waitcnt vmcnt(2)
	s_nop 3
	v_add_f32_e32 v74, v104, v74
	v_mul_f32_e32 v74, 0xbfb8aa3b, v74
	v_exp_f32_e32 v74, v74
	s_nop 0
	v_add_f32_e32 v74, 1.0, v74
	v_rcp_f32_e32 v74, v74
	s_nop 0
	v_mul_f32_e32 v74, 0xc1000000, v74
	v_mul_f32_e32 v93, v106, v74
	v_add_f32_e32 v74, v93, v93
	v_cmp_nlt_f32_e32 vcc, s68, v74
	s_and_saveexec_b64 s[2:3], vcc
	s_xor_b64 s[22:23], exec, s[2:3]
	v_mul_f32_e32 v74, 0x3fb8aa3b, v74
	v_exp_f32_e32 v74, v74
	s_nop 0
	v_sub_f32_e32 v94, 1.0, v74
	s_andn2_saveexec_b64 s[22:23], s[22:23]
	v_fmamk_f32 v79, v74, 0x3c088889, v197
	v_fmaak_f32 v79, v74, v79, 0x3e2aaaab
	v_fma_f32 v79, v74, v79, 0.5
	v_fma_f32 v79, v74, v79, 1.0
	v_mul_f32_e64 v94, v79, -v74
	s_or_b64 exec, exec, s[22:23]
	v_add_f32_e32 v74, v104, v75
	v_mul_f32_e32 v74, 0xbfb8aa3b, v74
	v_exp_f32_e32 v74, v74
	v_mul_u32_u24_e32 v132, 0x1040, v91
	v_add_u32_e32 v150, v168, v132
	ds_read_u16 v95, v150 offset:1040
	v_add_f32_e32 v74, 1.0, v74
	v_rcp_f32_e32 v74, v74
	s_nop 0
	v_mul_f32_e32 v74, 0xc1000000, v74
	v_mul_f32_e32 v98, v106, v74
	v_add_f32_e32 v74, v98, v98
	v_cmp_nlt_f32_e32 vcc, s68, v74
	s_and_saveexec_b64 s[2:3], vcc
	s_xor_b64 s[22:23], exec, s[2:3]
	v_mul_f32_e32 v74, 0x3fb8aa3b, v74
	v_exp_f32_e32 v74, v74
	s_nop 0
	v_sub_f32_e32 v99, 1.0, v74
	s_andn2_saveexec_b64 s[22:23], s[22:23]
	v_fmamk_f32 v75, v74, 0x3c088889, v197
	v_fmaak_f32 v75, v74, v75, 0x3e2aaaab
	v_fma_f32 v75, v74, v75, 0.5
	v_fma_f32 v75, v74, v75, 1.0
	v_mul_f32_e64 v99, v75, -v74
	s_or_b64 exec, exec, s[22:23]
	v_add_f32_e32 v74, v104, v76
	v_mul_f32_e32 v74, 0xbfb8aa3b, v74
	v_exp_f32_e32 v74, v74
	ds_read_u16 v102, v150 offset:2080
	v_add_f32_e32 v74, 1.0, v74
	v_rcp_f32_e32 v74, v74
	s_nop 0
	v_mul_f32_e32 v74, 0xc1000000, v74
	v_mul_f32_e32 v103, v106, v74
	v_add_f32_e32 v74, v103, v103
	v_cmp_nlt_f32_e32 vcc, s68, v74
	s_and_saveexec_b64 s[2:3], vcc
	s_xor_b64 s[22:23], exec, s[2:3]
	v_mul_f32_e32 v74, 0x3fb8aa3b, v74
	v_exp_f32_e32 v74, v74
	s_nop 0
	v_sub_f32_e32 v105, 1.0, v74
	s_andn2_saveexec_b64 s[22:23], s[22:23]
	v_fmamk_f32 v75, v74, 0x3c088889, v197
	v_fmaak_f32 v75, v74, v75, 0x3e2aaaab
	v_fma_f32 v75, v74, v75, 0.5
	v_fma_f32 v75, v74, v75, 1.0
	v_mul_f32_e64 v105, v75, -v74
	s_or_b64 exec, exec, s[22:23]
	v_add_f32_e32 v74, v104, v77
	v_mul_f32_e32 v74, 0xbfb8aa3b, v74
	v_exp_f32_e32 v74, v74
	ds_read_u16 v109, v150 offset:3120
	v_add_f32_e32 v74, 1.0, v74
	v_rcp_f32_e32 v74, v74
	s_nop 0
	v_mul_f32_e32 v74, 0xc1000000, v74
	v_mul_f32_e32 v113, v106, v74
	v_add_f32_e32 v74, v113, v113
	v_cmp_nlt_f32_e32 vcc, s68, v74
	s_and_saveexec_b64 s[2:3], vcc
	s_xor_b64 s[22:23], exec, s[2:3]
	v_mul_f32_e32 v74, 0x3fb8aa3b, v74
	v_exp_f32_e32 v74, v74
	s_nop 0
	v_sub_f32_e32 v114, 1.0, v74
	s_andn2_saveexec_b64 s[22:23], s[22:23]
	v_fmamk_f32 v75, v74, 0x3c088889, v197
	v_fmaak_f32 v75, v74, v75, 0x3e2aaaab
	v_fma_f32 v75, v74, v75, 0.5
	v_fma_f32 v75, v74, v75, 1.0
	v_mul_f32_e64 v114, v75, -v74
	s_or_b64 exec, exec, s[22:23]
	v_mul_u32_u24_e32 v74, 0x410, v1
	v_add_u32_e32 v135, v78, v74
	ds_read_b128 v[74:77], v135 offset:16640
	ds_read_b128 v[82:85], v135 offset:16704
	v_lshlrev_b32_e32 v108, 2, v91
	v_or_b32_e32 v100, 16, v108
	s_movk_i32 s2, 0x410
	s_waitcnt lgkmcnt(1)
	v_mfma_f32_16x16x32_bf16 v[78:81], v[74:77], v[66:69], 0
	s_waitcnt lgkmcnt(0)
; #define LAS __attribute__((address_space(3)))
; __device__ __forceinline__ float sigmoidf_(float v) { return __builtin_amdgcn_rcpf(1.0f + __builtin_amdgcn_exp2f(v * -1.4426950408889634f)); }
; template <bool FINAL> __device__ __forceinline__ void lru_unit(const Args& a, unsigned char* ws, int l, int unit, const LruW& W, LAS unsigned char* lds, int tid_in) {
;     ...
;         for (int mt = 0; mt < 4; ++mt) { pg8::f32x4 ra = {0.f, 0.f, 0.f, 0.f}, ri = {0.f, 0.f, 0.f, 0.f};
; #pragma unroll
;             for (int ks = 0; ks < 2; ++ks) { const bf16x8_t af = *(const LAS bf16x8_t*)(Xrm + (16 * mt + fr) * LR_RS + wave * 64 + 32 * ks + 8 * g);
;                 ra = __builtin_amdgcn_mfma_f32_16x16x32_bf16(af, W.wa[nt][ks], ra, 0, 0, 0); ri = __builtin_amdgcn_mfma_f32_16x16x32_bf16(af, W.wx[nt][ks], ri, 0, 0, 0); }
; #pragma unroll
;             for (int r = 0; r < 4; ++r) { const float rg = sigmoidf_(ra[r] + ba), ig = sigmoidf_(ri[r] + bx), la = -8.0f * rg * spn, xc = bf2f(Xrm[(16 * mt + 4 * g + r) * LR_RS + c]);
;                 const float x2 = 2.0f * la, em = (x2 > -0.25f) ? -x2 * (1.0f + x2 * (0.5f + x2 * (0.16666667f + x2 * (0.041666668f + x2 * 0.0083333338f)))) : 1.0f - __expf(x2);
;                 av[mt][r] = __expf(la); bv[mt][r] = __builtin_amdgcn_sqrtf(fmaxf(em, 0.f)) * (ig * xc); } }
	v_mfma_f32_16x16x32_bf16 v[78:81], v[82:85], v[58:61], v[78:81]
	v_mfma_f32_16x16x32_bf16 v[74:77], v[74:77], v[62:65], 0
	v_mfma_f32_16x16x32_bf16 v[74:77], v[82:85], v[54:57], v[74:77]
	s_nop 5
	v_add_f32_e32 v78, v104, v78
	v_mul_f32_e32 v78, 0xbfb8aa3b, v78
	v_exp_f32_e32 v78, v78
	v_mad_u32_u24 v82, v100, s2, v168
	ds_read_u16 v124, v82
	v_add_f32_e32 v78, 1.0, v78
	v_rcp_f32_e32 v78, v78
	s_nop 0
	v_mul_f32_e32 v78, 0xc1000000, v78
	v_mul_f32_e32 v125, v106, v78
	v_add_f32_e32 v78, v125, v125
	v_cmp_nlt_f32_e32 vcc, s68, v78
	s_and_saveexec_b64 s[2:3], vcc
	s_xor_b64 s[22:23], exec, s[2:3]
	v_mul_f32_e32 v78, 0x3fb8aa3b, v78
	v_exp_f32_e32 v78, v78
	s_nop 0
	v_sub_f32_e32 v126, 1.0, v78
	s_andn2_saveexec_b64 s[22:23], s[22:23]
	v_fmamk_f32 v82, v78, 0x3c088889, v197
	v_fmaak_f32 v82, v78, v82, 0x3e2aaaab
	v_fma_f32 v82, v78, v82, 0.5
	v_fma_f32 v82, v78, v82, 1.0
	v_mul_f32_e64 v126, v82, -v78
	s_or_b64 exec, exec, s[22:23]
	v_add_f32_e32 v78, v104, v79
	v_mul_f32_e32 v78, 0xbfb8aa3b, v78
	v_exp_f32_e32 v78, v78
	ds_read_u16 v111, v150 offset:17680
	v_add_f32_e32 v78, 1.0, v78
	v_rcp_f32_e32 v78, v78
	s_nop 0
	v_mul_f32_e32 v78, 0xc1000000, v78
	v_mul_f32_e32 v115, v106, v78
	v_add_f32_e32 v78, v115, v115
	v_cmp_nlt_f32_e32 vcc, s68, v78
	s_and_saveexec_b64 s[2:3], vcc
	s_xor_b64 s[22:23], exec, s[2:3]
	v_mul_f32_e32 v78, 0x3fb8aa3b, v78
	v_exp_f32_e32 v78, v78
	s_nop 0
	v_sub_f32_e32 v127, 1.0, v78
	s_andn2_saveexec_b64 s[22:23], s[22:23]
	v_fmamk_f32 v79, v78, 0x3c088889, v197
	v_fmaak_f32 v79, v78, v79, 0x3e2aaaab
	v_fma_f32 v79, v78, v79, 0.5
	v_fma_f32 v79, v78, v79, 1.0
	v_mul_f32_e64 v127, v79, -v78
	s_or_b64 exec, exec, s[22:23]
	v_add_f32_e32 v78, v104, v80
	v_mul_f32_e32 v78, 0xbfb8aa3b, v78
	v_exp_f32_e32 v78, v78
	ds_read_u16 v107, v150 offset:18720
	v_add_f32_e32 v78, 1.0, v78
	v_rcp_f32_e32 v78, v78
	s_nop 0
	v_mul_f32_e32 v78, 0xc1000000, v78
	v_mul_f32_e32 v128, v106, v78
	v_add_f32_e32 v78, v128, v128
	v_cmp_nlt_f32_e32 vcc, s68, v78
	s_and_saveexec_b64 s[2:3], vcc
	s_xor_b64 s[22:23], exec, s[2:3]
	v_mul_f32_e32 v78, 0x3fb8aa3b, v78
	v_exp_f32_e32 v78, v78
	s_nop 0
	v_sub_f32_e32 v129, 1.0, v78
	s_andn2_saveexec_b64 s[22:23], s[22:23]
	v_fmamk_f32 v79, v78, 0x3c088889, v197
	v_fmaak_f32 v79, v78, v79, 0x3e2aaaab
	v_fma_f32 v79, v78, v79, 0.5
	v_fma_f32 v79, v78, v79, 1.0
	v_mul_f32_e64 v129, v79, -v78
	s_or_b64 exec, exec, s[22:23]
	v_add_f32_e32 v78, v104, v81
	v_mul_f32_e32 v78, 0xbfb8aa3b, v78
	v_exp_f32_e32 v78, v78
	ds_read_u16 v130, v150 offset:19760
	v_add_f32_e32 v78, 1.0, v78
	v_rcp_f32_e32 v78, v78
	s_nop 0
	v_mul_f32_e32 v78, 0xc1000000, v78
	v_mul_f32_e32 v131, v106, v78
	v_add_f32_e32 v78, v131, v131
	v_cmp_nlt_f32_e32 vcc, s68, v78
	s_and_saveexec_b64 s[2:3], vcc
	s_xor_b64 s[22:23], exec, s[2:3]
	v_mul_f32_e32 v78, 0x3fb8aa3b, v78
	v_exp_f32_e32 v78, v78
	s_nop 0
	v_sub_f32_e32 v134, 1.0, v78
	s_andn2_saveexec_b64 s[22:23], s[22:23]
	v_fmamk_f32 v79, v78, 0x3c088889, v197
	v_fmaak_f32 v79, v78, v79, 0x3e2aaaab
	v_fma_f32 v79, v78, v79, 0.5
	v_fma_f32 v79, v78, v79, 1.0
	v_mul_f32_e64 v134, v79, -v78
	s_or_b64 exec, exec, s[22:23]
	ds_read_b128 v[78:81], v135 offset:33280
	ds_read_b128 v[86:89], v135 offset:33344
	v_mul_u32_u24_e32 v133, 0x410, v100
	v_add_u32_e32 v140, 0x4100, v133
	v_add_u32_e32 v156, v168, v140
	s_waitcnt lgkmcnt(1)
	v_mfma_f32_16x16x32_bf16 v[82:85], v[78:81], v[66:69], 0
	ds_read_u16 v136, v156
	s_waitcnt lgkmcnt(1)
	v_mfma_f32_16x16x32_bf16 v[82:85], v[86:89], v[58:61], v[82:85]
	v_mfma_f32_16x16x32_bf16 v[78:81], v[78:81], v[62:65], 0
	v_mfma_f32_16x16x32_bf16 v[78:81], v[86:89], v[54:57], v[78:81]
	s_nop 5
	v_add_f32_e32 v82, v104, v82
	v_mul_f32_e32 v82, 0xbfb8aa3b, v82
	v_exp_f32_e32 v82, v82
	s_nop 0
	v_add_f32_e32 v82, 1.0, v82
	v_rcp_f32_e32 v82, v82
	s_nop 0
	v_mul_f32_e32 v82, 0xc1000000, v82
	v_mul_f32_e32 v137, v106, v82
	v_add_f32_e32 v82, v137, v137
	v_cmp_nlt_f32_e32 vcc, s68, v82
	s_and_saveexec_b64 s[2:3], vcc
	s_xor_b64 s[22:23], exec, s[2:3]
	v_mul_f32_e32 v82, 0x3fb8aa3b, v82
	v_exp_f32_e32 v82, v82
	s_nop 0
	v_sub_f32_e32 v138, 1.0, v82
	s_andn2_saveexec_b64 s[22:23], s[22:23]
	v_fmamk_f32 v86, v82, 0x3c088889, v197
	v_fmaak_f32 v86, v82, v86, 0x3e2aaaab
	v_fma_f32 v86, v82, v86, 0.5
	v_fma_f32 v86, v82, v86, 1.0
	v_mul_f32_e64 v138, v86, -v82
	s_or_b64 exec, exec, s[22:23]
	v_add_f32_e32 v82, v104, v83
	v_mul_f32_e32 v82, 0xbfb8aa3b, v82
	v_exp_f32_e32 v82, v82
	ds_read_u16 v110, v150 offset:34320
	v_add_f32_e32 v82, 1.0, v82
	v_rcp_f32_e32 v82, v82
	s_nop 0
	v_mul_f32_e32 v82, 0xc1000000, v82
	v_mul_f32_e32 v143, v106, v82
	v_add_f32_e32 v82, v143, v143
	v_cmp_nlt_f32_e32 vcc, s68, v82
	s_and_saveexec_b64 s[2:3], vcc
	s_xor_b64 s[22:23], exec, s[2:3]
	v_mul_f32_e32 v82, 0x3fb8aa3b, v82
	v_exp_f32_e32 v82, v82
	s_nop 0
	v_sub_f32_e32 v144, 1.0, v82
	s_andn2_saveexec_b64 s[22:23], s[22:23]
	v_fmamk_f32 v83, v82, 0x3c088889, v197
	v_fmaak_f32 v83, v82, v83, 0x3e2aaaab
	v_fma_f32 v83, v82, v83, 0.5
	v_fma_f32 v83, v82, v83, 1.0
	v_mul_f32_e64 v144, v83, -v82
	s_or_b64 exec, exec, s[22:23]
	v_add_f32_e32 v82, v104, v84
	v_mul_f32_e32 v82, 0xbfb8aa3b, v82
	v_exp_f32_e32 v82, v82
	ds_read_u16 v112, v150 offset:35360
	v_add_f32_e32 v82, 1.0, v82
	v_rcp_f32_e32 v82, v82
	s_nop 0
	v_mul_f32_e32 v82, 0xc1000000, v82
	v_mul_f32_e32 v147, v106, v82
	v_add_f32_e32 v82, v147, v147
	v_cmp_nlt_f32_e32 vcc, s68, v82
	s_and_saveexec_b64 s[2:3], vcc
	s_xor_b64 s[22:23], exec, s[2:3]
	v_mul_f32_e32 v82, 0x3fb8aa3b, v82
	v_exp_f32_e32 v82, v82
	s_nop 0
	v_sub_f32_e32 v148, 1.0, v82
	s_andn2_saveexec_b64 s[22:23], s[22:23]
	v_fmamk_f32 v83, v82, 0x3c088889, v197
	v_fmaak_f32 v83, v82, v83, 0x3e2aaaab
	v_fma_f32 v83, v82, v83, 0.5
	v_fma_f32 v83, v82, v83, 1.0
	v_mul_f32_e64 v148, v83, -v82
	s_or_b64 exec, exec, s[22:23]
	v_add_f32_e32 v82, v104, v85
	v_mul_f32_e32 v82, 0xbfb8aa3b, v82
	v_exp_f32_e32 v82, v82
	ds_read_u16 v149, v150 offset:36400
	v_add_f32_e32 v82, 1.0, v82
	v_rcp_f32_e32 v82, v82
	s_nop 0
	v_mul_f32_e32 v82, 0xc1000000, v82
	v_mul_f32_e32 v151, v106, v82
	v_add_f32_e32 v82, v151, v151
	v_cmp_nlt_f32_e32 vcc, s68, v82
	s_and_saveexec_b64 s[2:3], vcc
	s_xor_b64 s[22:23], exec, s[2:3]
	v_mul_f32_e32 v82, 0x3fb8aa3b, v82
	v_exp_f32_e32 v82, v82
	s_nop 0
	v_sub_f32_e32 v152, 1.0, v82
	s_andn2_saveexec_b64 s[22:23], s[22:23]
	v_fmamk_f32 v83, v82, 0x3c088889, v197
	v_fmaak_f32 v83, v82, v83, 0x3e2aaaab
	v_fma_f32 v83, v82, v83, 0.5
	v_fma_f32 v83, v82, v83, 1.0
	v_mul_f32_e64 v152, v83, -v82
	s_or_b64 exec, exec, s[22:23]
	ds_read_b128 v[82:85], v135 offset:49920
	ds_read_b128 v[170:173], v135 offset:49984
	v_add_u32_e32 v141, 0x4100, v140
	v_add_u32_e32 v157, v168, v141
	ds_read_u16 v153, v157
	s_waitcnt lgkmcnt(2)
; #define LAS __attribute__((address_space(3)))
; __device__ __forceinline__ float sigmoidf_(float v) { return __builtin_amdgcn_rcpf(1.0f + __builtin_amdgcn_exp2f(v * -1.4426950408889634f)); }
; template <bool FINAL> __device__ __forceinline__ void lru_unit(const Args& a, unsigned char* ws, int l, int unit, const LruW& W, LAS unsigned char* lds, int tid_in) {
;     ...
;             for (int ks = 0; ks < 2; ++ks) { const bf16x8_t af = *(const LAS bf16x8_t*)(Xrm + (16 * mt + fr) * LR_RS + wave * 64 + 32 * ks + 8 * g);
;                 ra = __builtin_amdgcn_mfma_f32_16x16x32_bf16(af, W.wa[nt][ks], ra, 0, 0, 0); ri = __builtin_amdgcn_mfma_f32_16x16x32_bf16(af, W.wx[nt][ks], ri, 0, 0, 0); }
; #pragma unroll
;             for (int r = 0; r < 4; ++r) { const float rg = sigmoidf_(ra[r] + ba), ig = sigmoidf_(ri[r] + bx), la = -8.0f * rg * spn, xc = bf2f(Xrm[(16 * mt + 4 * g + r) * LR_RS + c]);
;                 const float x2 = 2.0f * la, em = (x2 > -0.25f) ? -x2 * (1.0f + x2 * (0.5f + x2 * (0.16666667f + x2 * (0.041666668f + x2 * 0.0083333338f)))) : 1.0f - __expf(x2);
;                 av[mt][r] = __expf(la); bv[mt][r] = __builtin_amdgcn_sqrtf(fmaxf(em, 0.f)) * (ig * xc); } }
	v_mfma_f32_16x16x32_bf16 v[86:89], v[82:85], v[66:69], 0
	s_waitcnt lgkmcnt(1)
	v_mfma_f32_16x16x32_bf16 v[86:89], v[170:173], v[58:61], v[86:89]
	v_mfma_f32_16x16x32_bf16 v[82:85], v[82:85], v[62:65], 0
	v_mfma_f32_16x16x32_bf16 v[82:85], v[170:173], v[54:57], v[82:85]
	s_nop 5
	v_add_f32_e32 v86, v104, v86
	v_mul_f32_e32 v86, 0xbfb8aa3b, v86
	v_exp_f32_e32 v86, v86
	s_nop 0
	v_add_f32_e32 v86, 1.0, v86
	v_rcp_f32_e32 v86, v86
	s_nop 0
	v_mul_f32_e32 v86, 0xc1000000, v86
	v_mul_f32_e32 v154, v106, v86
	v_add_f32_e32 v86, v154, v154
	v_cmp_nlt_f32_e32 vcc, s68, v86
	s_and_saveexec_b64 s[2:3], vcc
	s_xor_b64 s[22:23], exec, s[2:3]
	v_mul_f32_e32 v86, 0x3fb8aa3b, v86
	v_exp_f32_e32 v86, v86
	s_nop 0
	v_sub_f32_e32 v155, 1.0, v86
	s_andn2_saveexec_b64 s[22:23], s[22:23]
	v_fmamk_f32 v139, v86, 0x3c088889, v197
	v_fmaak_f32 v139, v86, v139, 0x3e2aaaab
	v_fma_f32 v139, v86, v139, 0.5
	v_fma_f32 v139, v86, v139, 1.0
	v_mul_f32_e64 v155, v139, -v86
	s_or_b64 exec, exec, s[22:23]
	v_add_f32_e32 v86, v104, v87
	v_mul_f32_e32 v86, 0xbfb8aa3b, v86
	v_exp_f32_e32 v86, v86
	ds_read_u16 v87, v150 offset:50960
	v_add_f32_e32 v86, 1.0, v86
	v_rcp_f32_e32 v86, v86
	s_nop 0
	v_mul_f32_e32 v86, 0xc1000000, v86
	v_mul_f32_e32 v158, v106, v86
	v_add_f32_e32 v86, v158, v158
	v_cmp_nlt_f32_e32 vcc, s68, v86
	s_and_saveexec_b64 s[2:3], vcc
	s_xor_b64 s[22:23], exec, s[2:3]
	v_mul_f32_e32 v86, 0x3fb8aa3b, v86
	v_exp_f32_e32 v86, v86
	s_nop 0
	v_sub_f32_e32 v163, 1.0, v86
	s_andn2_saveexec_b64 s[22:23], s[22:23]
	v_fmamk_f32 v139, v86, 0x3c088889, v197
	v_fmaak_f32 v139, v86, v139, 0x3e2aaaab
	v_fma_f32 v139, v86, v139, 0.5
	v_fma_f32 v139, v86, v139, 1.0
	v_mul_f32_e64 v163, v139, -v86
	s_or_b64 exec, exec, s[22:23]
	v_add_f32_e32 v86, v104, v88
	v_mul_f32_e32 v86, 0xbfb8aa3b, v86
	v_exp_f32_e32 v86, v86
	s_nop 0
	v_add_f32_e32 v86, 1.0, v86
	v_rcp_f32_e32 v88, v86
	ds_read_u16 v86, v150 offset:52000
	v_mul_f32_e32 v88, 0xc1000000, v88
	v_mul_f32_e32 v88, v106, v88
	v_add_f32_e32 v139, v88, v88
	v_cmp_nlt_f32_e32 vcc, s68, v139
	s_and_saveexec_b64 s[2:3], vcc
	s_xor_b64 s[22:23], exec, s[2:3]
	v_mul_f32_e32 v139, 0x3fb8aa3b, v139
	v_exp_f32_e32 v139, v139
	s_nop 0
	v_sub_f32_e32 v145, 1.0, v139
	s_andn2_saveexec_b64 s[22:23], s[22:23]
	v_fmamk_f32 v142, v139, 0x3c088889, v197
	v_fmaak_f32 v142, v139, v142, 0x3e2aaaab
	v_fma_f32 v142, v139, v142, 0.5
	v_fma_f32 v142, v139, v142, 1.0
	v_mul_f32_e64 v145, v142, -v139
	s_or_b64 exec, exec, s[22:23]
	v_add_f32_e32 v89, v104, v89
	v_mul_f32_e32 v89, 0xbfb8aa3b, v89
	v_exp_f32_e32 v89, v89
	s_nop 0
	v_add_f32_e32 v89, 1.0, v89
	v_rcp_f32_e32 v104, v89
	ds_read_u16 v89, v150 offset:53040
	v_mul_f32_e32 v104, 0xc1000000, v104
	v_mul_f32_e32 v139, v106, v104
	v_add_f32_e32 v104, v139, v139
	v_cmp_nlt_f32_e32 vcc, s68, v104
	s_and_saveexec_b64 s[2:3], vcc
	s_xor_b64 s[22:23], exec, s[2:3]
	v_mul_f32_e32 v104, 0x3fb8aa3b, v104
	v_exp_f32_e32 v104, v104
	s_nop 0
	v_sub_f32_e32 v142, 1.0, v104
	s_andn2_saveexec_b64 s[22:23], s[22:23]
	v_fmamk_f32 v106, v104, 0x3c088889, v197
	v_fmaak_f32 v106, v104, v106, 0x3e2aaaab
	v_fma_f32 v106, v104, v106, 0.5
	v_fma_f32 v106, v104, v106, 1.0
	v_mul_f32_e64 v142, v106, -v104
	s_or_b64 exec, exec, s[22:23]
	s_waitcnt vmcnt(1)
	v_add_f32_e32 v84, v90, v84
	v_mul_f32_e32 v84, 0xbfb8aa3b, v84
	v_exp_f32_e32 v84, v84
	s_waitcnt lgkmcnt(1)
	v_lshlrev_b32_e32 v104, 16, v86
	v_mul_f32_e32 v86, 0x3fb8aa3b, v88
	v_max_f32_e32 v88, v145, v145
	v_add_f32_e32 v84, 1.0, v84
	v_add_f32_e32 v83, v90, v83
	v_rcp_f32_e32 v84, v84
	v_max_f32_e32 v88, 0, v88
	v_mul_f32_e32 v83, 0xbfb8aa3b, v83
	v_sqrt_f32_e32 v88, v88
	v_exp_f32_e32 v83, v83
	v_add_f32_e32 v82, v90, v82
	v_mul_f32_e32 v82, 0xbfb8aa3b, v82
	v_add_f32_e32 v81, v90, v81
	v_exp_f32_e32 v82, v82
	v_mul_f32_e32 v81, 0xbfb8aa3b, v81
	v_mul_f32_e32 v84, v84, v104
	v_exp_f32_e32 v81, v81
	v_add_f32_e32 v80, v90, v80
	v_mul_f32_e32 v84, v84, v88
	v_add_f32_e32 v83, 1.0, v83
	v_max_f32_e32 v88, v163, v163
	v_mul_f32_e32 v80, 0xbfb8aa3b, v80
	v_add_f32_e32 v79, v90, v79
	v_rcp_f32_e32 v83, v83
	v_max_f32_e32 v88, 0, v88
	v_exp_f32_e32 v80, v80
	v_mul_f32_e32 v79, 0xbfb8aa3b, v79
	v_add_f32_e32 v78, v90, v78
	v_sqrt_f32_e32 v88, v88
	v_add_f32_e32 v82, 1.0, v82
	v_exp_f32_e32 v79, v79
	v_mul_f32_e32 v78, 0xbfb8aa3b, v78
	v_add_f32_e32 v77, v90, v77
	v_rcp_f32_e32 v82, v82
	v_add_f32_e32 v81, 1.0, v81
	v_max_f32_e32 v104, v152, v152
	v_exp_f32_e32 v78, v78
	v_mul_f32_e32 v77, 0xbfb8aa3b, v77
	v_lshlrev_b32_e32 v87, 16, v87
	v_rcp_f32_e32 v81, v81
	v_max_f32_e32 v104, 0, v104
	v_exp_f32_e32 v77, v77
	v_mul_f32_e32 v83, v83, v87
	v_sqrt_f32_e32 v104, v104
	v_add_f32_e32 v80, 1.0, v80
	v_mul_f32_e32 v83, v83, v88
	v_lshlrev_b32_e32 v88, 16, v153
	v_rcp_f32_e32 v80, v80
	v_add_f32_e32 v79, 1.0, v79
	v_mul_f32_e32 v82, v82, v88
	v_lshlrev_b32_e32 v88, 16, v149
	v_rcp_f32_e32 v79, v79
	v_add_f32_e32 v78, 1.0, v78
	v_add_f32_e32 v76, v90, v76
	v_mul_f32_e32 v81, v81, v88
	v_rcp_f32_e32 v78, v78
	v_add_f32_e32 v77, 1.0, v77
	v_mul_f32_e32 v76, 0xbfb8aa3b, v76
	v_mul_f32_e32 v88, v81, v104
	v_lshlrev_b32_e32 v104, 16, v112
	v_rcp_f32_e32 v77, v77
	v_exp_f32_e32 v76, v76
	v_mul_f32_e32 v80, v80, v104
	v_lshlrev_b32_e32 v104, 16, v110
	v_add_f32_e32 v75, v90, v75
	v_mul_f32_e32 v79, v79, v104
	v_lshlrev_b32_e32 v104, 16, v136
	v_mul_f32_e32 v75, 0xbfb8aa3b, v75
	v_mul_f32_e32 v78, v78, v104
	v_lshlrev_b32_e32 v104, 16, v130
	v_exp_f32_e32 v75, v75
	v_mul_f32_e32 v77, v77, v104
	v_add_f32_e32 v76, 1.0, v76
	v_mul_f32_e32 v104, 0x3fb8aa3b, v128
	v_max_f32_e32 v128, v129, v129
	v_rcp_f32_e32 v76, v76
	v_max_f32_e32 v128, 0, v128
	v_sqrt_f32_e32 v128, v128
; __device__ __forceinline__ float sigmoidf_(float v) { return __builtin_amdgcn_rcpf(1.0f + __builtin_amdgcn_exp2f(v * -1.4426950408889634f)); }
; template <bool FINAL> __device__ __forceinline__ void lru_unit(const Args& a, unsigned char* ws, int l, int unit, const LruW& W, LAS unsigned char* lds, int tid_in) {
;     ...
;             for (int r = 0; r < 4; ++r) { const float rg = sigmoidf_(ra[r] + ba), ig = sigmoidf_(ri[r] + bx), la = -8.0f * rg * spn, xc = bf2f(Xrm[(16 * mt + 4 * g + r) * LR_RS + c]);
;                 const float x2 = 2.0f * la, em = (x2 > -0.25f) ? -x2 * (1.0f + x2 * (0.5f + x2 * (0.16666667f + x2 * (0.041666668f + x2 * 0.0083333338f)))) : 1.0f - __expf(x2);
;                 av[mt][r] = __expf(la); bv[mt][r] = __builtin_amdgcn_sqrtf(fmaxf(em, 0.f)) * (ig * xc); } }
;         float carry = carry0, atot = 1.f;
; #pragma unroll
;         for (int mt = 0; mt < 4; ++mt) {
;             float As = av[mt][0], Hs = bv[mt][0];
; #pragma unroll
;             for (int r = 1; r < 4; ++r) { Hs = av[mt][r] * Hs + bv[mt][r]; As *= av[mt][r]; }
;             float Ai = As, Hi = Hs;
;             { const float Ap = __shfl_up(Ai, 16), Hp = __shfl_up(Hi, 16); if (g >= 1) { Hi = Ai * Hp + Hi; Ai = Ai * Ap; } }
;             { const float Ap = __shfl_up(Ai, 32), Hp = __shfl_up(Hi, 32); if (g >= 2) { Hi = Ai * Hp + Hi; Ai = Ai * Ap; } }
;             float Ae = __shfl_up(Ai, 16), He = __shfl_up(Hi, 16); if (g == 0) { Ae = 1.f; He = 0.f; }
;             const float At = __shfl(Ai, fr + 48), Ht = __shfl(Hi, fr + 48);
	v_add_f32_e32 v75, 1.0, v75
	v_add_f32_e32 v74, v90, v74
	v_lshlrev_b32_e32 v107, 16, v107
	v_rcp_f32_e32 v75, v75
	v_mul_f32_e32 v74, 0xbfb8aa3b, v74
	v_mul_f32_e32 v76, v76, v107
	v_exp_f32_e32 v74, v74
	v_add_f32_e32 v73, v90, v73
	v_mul_f32_e32 v107, v76, v128
	v_lshlrev_b32_e32 v76, 16, v111
	v_mul_f32_e32 v111, 0x3fb8aa3b, v115
	v_mul_f32_e32 v73, 0xbfb8aa3b, v73
	v_exp_f32_e32 v115, v111
	v_max_f32_e32 v111, v127, v127
	v_exp_f32_e32 v73, v73
	v_max_f32_e32 v111, 0, v111
	v_mul_f32_e32 v75, v75, v76
	v_mul_f32_e32 v76, 0x3fb8aa3b, v125
	v_sqrt_f32_e32 v111, v111
	v_add_f32_e32 v74, 1.0, v74
	v_exp_f32_e32 v127, v76
	v_max_f32_e32 v76, v126, v126
	v_rcp_f32_e32 v74, v74
	v_max_f32_e32 v76, 0, v76
	v_sqrt_f32_e32 v76, v76
	v_add_f32_e32 v73, 1.0, v73
	v_add_f32_e32 v72, v90, v72
	v_rcp_f32_e32 v73, v73
	v_mul_f32_e32 v72, 0xbfb8aa3b, v72
	v_mul_f32_e32 v111, v75, v111
	v_lshlrev_b32_e32 v75, 16, v124
	v_exp_f32_e32 v72, v72
	v_mul_f32_e32 v74, v74, v75
	v_mul_f32_e32 v75, 0x3fb8aa3b, v113
	v_mul_f32_e32 v125, v74, v76
	v_lshlrev_b32_e32 v74, 16, v109
	v_exp_f32_e32 v124, v75
	v_max_f32_e32 v75, v114, v114
	v_max_f32_e32 v75, 0, v75
	v_mul_f32_e32 v73, v73, v74
	v_mul_f32_e32 v74, 0x3fb8aa3b, v103
	v_sqrt_f32_e32 v75, v75
	v_add_f32_e32 v72, 1.0, v72
	v_exp_f32_e32 v114, v74
	v_max_f32_e32 v74, v105, v105
	v_add_f32_e32 v71, v90, v71
	v_rcp_f32_e32 v72, v72
	v_max_f32_e32 v74, 0, v74
	v_mul_f32_e32 v71, 0xbfb8aa3b, v71
	v_sqrt_f32_e32 v74, v74
	v_exp_f32_e32 v71, v71
	v_mul_f32_e32 v113, v73, v75
	v_lshlrev_b32_e32 v73, 16, v102
	v_mul_f32_e32 v72, v72, v73
	v_mul_f32_e32 v73, 0x3fb8aa3b, v98
	v_mul_f32_e32 v103, v72, v74
	v_add_f32_e32 v71, 1.0, v71
	v_lshlrev_b32_e32 v72, 16, v95
	v_exp_f32_e32 v95, v73
	v_max_f32_e32 v73, v99, v99
	v_add_f32_e32 v70, v90, v70
	v_rcp_f32_e32 v71, v71
	v_max_f32_e32 v73, 0, v73
	v_mul_f32_e32 v70, 0xbfb8aa3b, v70
	v_sqrt_f32_e32 v73, v73
	v_exp_f32_e32 v70, v70
	v_mul_f32_e32 v106, 0x3fb8aa3b, v147
	v_exp_f32_e32 v112, v106
	v_max_f32_e32 v106, v148, v148
	v_mul_f32_e32 v71, v71, v72
	v_max_f32_e32 v106, 0, v106
	v_mul_f32_e32 v98, v71, v73
	v_add_f32_e32 v70, 1.0, v70
	v_max_f32_e32 v73, v94, v94
	v_sqrt_f32_e32 v106, v106
	v_rcp_f32_e32 v70, v70
	v_max_f32_e32 v73, 0, v73
	v_sqrt_f32_e32 v73, v73
	v_lshlrev_b32_e32 v71, 16, v92
	v_mul_f32_e32 v80, v80, v106
	v_mul_f32_e32 v106, 0x3fb8aa3b, v143
	v_mul_f32_e32 v70, v70, v71
	v_exp_f32_e32 v110, v106
	v_max_f32_e32 v106, v144, v144
	v_max_f32_e32 v130, v134, v134
	v_mul_f32_e32 v94, v70, v73
	v_add_u32_e32 v70, -16, v199
	v_and_b32_e32 v134, 64, v199
	v_max_f32_e32 v106, 0, v106
	v_cmp_lt_i32_e32 vcc, v70, v134
	v_add_f32_e32 v85, v90, v85
	v_sqrt_f32_e32 v106, v106
	v_cndmask_b32_e32 v70, v70, v199, vcc
	v_mul_f32_e32 v85, 0xbfb8aa3b, v85
	v_lshlrev_b32_e32 v136, 2, v70
	v_subrev_u32_e32 v70, 32, v199
	v_exp_f32_e32 v85, v85
	v_cmp_lt_i32_e64 s[36:37], v70, v134
	v_mul_f32_e32 v79, v79, v106
	v_mul_f32_e32 v106, 0x3fb8aa3b, v137
	v_cndmask_b32_e64 v70, v70, v199, s[36:37]
	v_lshlrev_b32_e32 v137, 2, v70
	v_or_b32_e32 v70, v134, v1
	v_lshlrev_b32_e32 v169, 2, v70
	v_mul_f32_e32 v70, 0x3fb8aa3b, v139
	v_add_f32_e32 v85, 1.0, v85
	v_exp_f32_e32 v76, v70
	v_max_f32_e32 v70, v142, v142
	v_rcp_f32_e32 v145, v85
	v_mul_f32_e32 v72, 0x3fb8aa3b, v93
	v_max_f32_e32 v70, 0, v70
	v_exp_f32_e32 v72, v72
	v_sqrt_f32_e32 v70, v70
	s_waitcnt lgkmcnt(0)
	v_lshlrev_b32_e32 v146, 16, v89
	v_mul_f32_e32 v71, v145, v146
	v_cmp_eq_u32_e32 vcc, 0, v91
	v_mul_f32_e32 v74, v71, v70
	v_fma_f32 v70, v95, v94, v98
	v_mul_f32_e32 v71, v72, v95
	v_fma_f32 v70, v114, v70, v103
	v_mul_f32_e32 v71, v114, v71
	v_fma_f32 v70, v124, v70, v113
	v_mul_f32_e32 v71, v124, v71
	ds_bpermute_b32 v73, v136, v71
	ds_bpermute_b32 v75, v136, v70
	v_cmp_lt_u32_e64 s[36:37], 1, v91
	v_or_b32_e32 v81, s44, v108
	v_readlane_b32 s2, v255, 11
	s_waitcnt lgkmcnt(1)
	v_mul_f32_e32 v73, v71, v73
	s_waitcnt lgkmcnt(0)
	v_fma_f32 v75, v71, v75, v70
	v_cndmask_b32_e32 v71, v73, v71, vcc
	v_cndmask_b32_e32 v70, v75, v70, vcc
	ds_bpermute_b32 v73, v137, v71
	ds_bpermute_b32 v75, v137, v70
	v_lshl_add_u32 v102, v96, 1, s2
	s_mul_i32 s2, s45, 0x3000
	s_mov_b64 s[4:5], 0x2c00
	s_waitcnt lgkmcnt(1)
	v_mul_f32_e32 v73, v71, v73
	s_waitcnt lgkmcnt(0)
	v_fma_f32 v75, v71, v75, v70
	v_cndmask_b32_e64 v71, v71, v73, s[36:37]
	v_cndmask_b32_e64 v70, v70, v75, s[36:37]
	ds_bpermute_b32 v73, v136, v71
	ds_bpermute_b32 v75, v136, v70
	ds_bpermute_b32 v105, v169, v71 offset:192
	ds_bpermute_b32 v109, v169, v70 offset:192
	v_mov_b64_e32 v[70:71], s[26:27]
	s_waitcnt lgkmcnt(3)
	v_cndmask_b32_e64 v73, v73, 1.0, vcc
	s_waitcnt lgkmcnt(2)
	v_cndmask_b32_e64 v75, v75, 0, vcc
	s_waitcnt vmcnt(0)
; __device__ __forceinline__ unsigned f2bf(float f) { return pk2(f, f) & 0xffffu; }
; __device__ __forceinline__ float sigmoidf_(float v) { return __builtin_amdgcn_rcpf(1.0f + __builtin_amdgcn_exp2f(v * -1.4426950408889634f)); }
; template <bool FINAL> __device__ __forceinline__ void lru_unit(const Args& a, unsigned char* ws, int l, int unit, const LruW& W, LAS unsigned char* lds, int tid_in) {
;     ...
;         for (int mt = 0; mt < 4; ++mt) {
;             float As = av[mt][0], Hs = bv[mt][0];
; #pragma unroll
;             for (int r = 1; r < 4; ++r) { Hs = av[mt][r] * Hs + bv[mt][r]; As *= av[mt][r]; }
;             float Ai = As, Hi = Hs;
;             { const float Ap = __shfl_up(Ai, 16), Hp = __shfl_up(Hi, 16); if (g >= 1) { Hi = Ai * Hp + Hi; Ai = Ai * Ap; } }
;             { const float Ap = __shfl_up(Ai, 32), Hp = __shfl_up(Hi, 32); if (g >= 2) { Hi = Ai * Hp + Hi; Ai = Ai * Ap; } }
;             float Ae = __shfl_up(Ai, 16), He = __shfl_up(Hi, 16); if (g == 0) { Ae = 1.f; He = 0.f; }
;             const float At = __shfl(Ai, fr + 48), Ht = __shfl(Hi, fr + 48);
;             if (FINAL) { float hc = Ae * carry + He;
; #pragma unroll
;                 for (int r = 0; r < 4; ++r) { hc = av[mt][r] * hc + bv[mt][r]; const float gt = bf2f(proj[(row0 + 16 * mt + 4 * g + r) * NPROJ + PC_DG + c]); const float u2 = 1.5957691216057308f * (gt + 0.044715f * gt * gt * gt); const float o = hc * gt * sigmoidf_(u2);
;                     Hrm[(16 * mt + 4 * g + r) * LR_RS + c] = (bf16)f2bf(o); ssp[mt][r] += o * o; } }
	v_fmac_f32_e32 v75, v101, v73
	v_fmac_f32_e32 v94, v72, v75
	v_mad_u64_u32 v[72:73], s[22:23], v81, s73, v[70:71]
	v_add_u32_e32 v73, s2, v73
	v_lshl_add_u64 v[90:91], v[72:73], 0, s[4:5]
	v_lshlrev_b64 v[72:73], 1, v[96:97]
	v_lshl_add_u64 v[92:93], v[90:91], 0, v[72:73]
	global_load_ushort v75, v[92:93], off
	v_or_b32_e32 v204, 1, v81
	v_mad_u64_u32 v[206:207], s[22:23], v204, s73, v[70:71]
	v_add_u32_e32 v207, s2, v207
	v_lshl_add_u64 v[206:207], v[206:207], 0, s[4:5]
	v_lshl_add_u64 v[206:207], v[206:207], 0, v[72:73]
	global_load_ushort v209, v[206:207], off
	v_or_b32_e32 v204, 2, v81
	v_mad_u64_u32 v[206:207], s[22:23], v204, s73, v[70:71]
	v_add_u32_e32 v207, s2, v207
	v_lshl_add_u64 v[206:207], v[206:207], 0, s[4:5]
	v_lshl_add_u64 v[206:207], v[206:207], 0, v[72:73]
	global_load_ushort v209, v[206:207], off
	v_or_b32_e32 v204, 3, v81
	v_mad_u64_u32 v[206:207], s[22:23], v204, s73, v[70:71]
	v_add_u32_e32 v207, s2, v207
	v_lshl_add_u64 v[206:207], v[206:207], 0, s[4:5]
	v_lshl_add_u64 v[206:207], v[206:207], 0, v[72:73]
	global_load_ushort v209, v[206:207], off
	v_or_b32_e32 v204, 16, v81
	v_mad_u64_u32 v[206:207], s[22:23], v204, s73, v[70:71]
	v_add_u32_e32 v207, s2, v207
	v_lshl_add_u64 v[206:207], v[206:207], 0, s[4:5]
	v_lshl_add_u64 v[206:207], v[206:207], 0, v[72:73]
	global_load_ushort v209, v[206:207], off
	v_or_b32_e32 v204, 17, v81
	v_mad_u64_u32 v[206:207], s[22:23], v204, s73, v[70:71]
	v_add_u32_e32 v207, s2, v207
	v_lshl_add_u64 v[206:207], v[206:207], 0, s[4:5]
	v_lshl_add_u64 v[206:207], v[206:207], 0, v[72:73]
	global_load_ushort v209, v[206:207], off
	v_or_b32_e32 v204, 18, v81
	v_mad_u64_u32 v[206:207], s[22:23], v204, s73, v[70:71]
	v_add_u32_e32 v207, s2, v207
	v_lshl_add_u64 v[206:207], v[206:207], 0, s[4:5]
	v_lshl_add_u64 v[206:207], v[206:207], 0, v[72:73]
	global_load_ushort v209, v[206:207], off
	v_or_b32_e32 v204, 19, v81
	v_mad_u64_u32 v[206:207], s[22:23], v204, s73, v[70:71]
	v_add_u32_e32 v207, s2, v207
	v_lshl_add_u64 v[206:207], v[206:207], 0, s[4:5]
	v_lshl_add_u64 v[206:207], v[206:207], 0, v[72:73]
	global_load_ushort v209, v[206:207], off
	v_or_b32_e32 v204, 32, v81
	v_mad_u64_u32 v[206:207], s[22:23], v204, s73, v[70:71]
	v_add_u32_e32 v207, s2, v207
	v_lshl_add_u64 v[206:207], v[206:207], 0, s[4:5]
	v_lshl_add_u64 v[206:207], v[206:207], 0, v[72:73]
	global_load_ushort v209, v[206:207], off
	v_or_b32_e32 v204, 33, v81
	v_mad_u64_u32 v[206:207], s[22:23], v204, s73, v[70:71]
	v_add_u32_e32 v207, s2, v207
	v_lshl_add_u64 v[206:207], v[206:207], 0, s[4:5]
	v_lshl_add_u64 v[206:207], v[206:207], 0, v[72:73]
	global_load_ushort v209, v[206:207], off
	v_or_b32_e32 v204, 34, v81
	v_mad_u64_u32 v[206:207], s[22:23], v204, s73, v[70:71]
	v_add_u32_e32 v207, s2, v207
	v_lshl_add_u64 v[206:207], v[206:207], 0, s[4:5]
	v_lshl_add_u64 v[206:207], v[206:207], 0, v[72:73]
	global_load_ushort v209, v[206:207], off
	v_or_b32_e32 v204, 35, v81
	v_mad_u64_u32 v[206:207], s[22:23], v204, s73, v[70:71]
	v_add_u32_e32 v207, s2, v207
	v_lshl_add_u64 v[206:207], v[206:207], 0, s[4:5]
	v_lshl_add_u64 v[206:207], v[206:207], 0, v[72:73]
	global_load_ushort v209, v[206:207], off
	v_or_b32_e32 v204, 48, v81
	v_mad_u64_u32 v[206:207], s[22:23], v204, s73, v[70:71]
	v_add_u32_e32 v207, s2, v207
	v_lshl_add_u64 v[206:207], v[206:207], 0, s[4:5]
	v_lshl_add_u64 v[206:207], v[206:207], 0, v[72:73]
	global_load_ushort v209, v[206:207], off
	v_or_b32_e32 v204, 49, v81
	v_mad_u64_u32 v[206:207], s[22:23], v204, s73, v[70:71]
	v_add_u32_e32 v207, s2, v207
	v_lshl_add_u64 v[206:207], v[206:207], 0, s[4:5]
	v_lshl_add_u64 v[206:207], v[206:207], 0, v[72:73]
	global_load_ushort v209, v[206:207], off
	v_or_b32_e32 v204, 50, v81
	v_mad_u64_u32 v[206:207], s[22:23], v204, s73, v[70:71]
	v_add_u32_e32 v207, s2, v207
	v_lshl_add_u64 v[206:207], v[206:207], 0, s[4:5]
	v_lshl_add_u64 v[206:207], v[206:207], 0, v[72:73]
	global_load_ushort v209, v[206:207], off
	v_or_b32_e32 v204, 51, v81
	v_mad_u64_u32 v[206:207], s[22:23], v204, s73, v[70:71]
	v_add_u32_e32 v207, s2, v207
	v_lshl_add_u64 v[206:207], v[206:207], 0, s[4:5]
	v_lshl_add_u64 v[206:207], v[206:207], 0, v[72:73]
	global_load_ushort v209, v[206:207], off
	v_mov_b32_e32 v204, 0x1800
	v_mov_b32_e32 v206, 0xf149f2ca
	v_mov_b32_e32 v207, 0x60
	v_fmac_f32_e32 v98, v95, v94
	v_exp_f32_e32 v108, v106
	v_max_f32_e32 v106, v138, v138
	v_fmac_f32_e32 v103, v114, v98
	v_fmac_f32_e32 v113, v124, v103
	v_max_f32_e32 v106, 0, v106
	v_sqrt_f32_e32 v106, v106
	v_max_f32_e32 v130, 0, v130
	v_sqrt_f32_e32 v130, v130
	v_exp_f32_e32 v104, v104
	v_mul_f32_e32 v78, v78, v106
	v_mul_f32_e32 v106, 0x3fb8aa3b, v131
	v_exp_f32_e32 v106, v106
	s_waitcnt lgkmcnt(0)
	v_fmac_f32_e32 v109, v101, v105
	v_mul_f32_e32 v101, v127, v115
	v_mul_f32_e32 v77, v77, v130
	v_mul_f32_e32 v101, v104, v101
	v_mul_f32_e32 v101, v106, v101
	v_max_f32_e32 v89, v155, v155
	v_max_f32_e32 v89, 0, v89
	v_sqrt_f32_e32 v89, v89
	v_mul_f32_e32 v85, 0x3fb8aa3b, v158
	v_mul_f32_e32 v87, 0x3fb8aa3b, v154
	v_exp_f32_e32 v85, v85
	v_mul_f32_e32 v82, v82, v89
	v_mul_f32_e32 v89, 0x3fb8aa3b, v151
	v_exp_f32_e32 v89, v89
	v_exp_f32_e32 v87, v87
	v_exp_f32_e32 v86, v86
	s_waitcnt vmcnt(0)
	v_mov_b32_e32 v209, 0xa000
	v_lshlrev_b32_e32 v75, 16, v75
	v_mul_f32_e32 v92, 0x3d372713, v75
	v_mul_f32_e32 v92, v92, v75
	v_fma_f32 v92, v92, v75, v75
	v_mul_f32_e32 v92, 0x3fcc422a, v92
	v_mul_f32_e32 v92, 0xbfb8aa3b, v92
	v_exp_f32_e32 v92, v92
	v_mul_f32_e32 v75, v94, v75
	v_add_f32_e32 v92, 1.0, v92
	v_rcp_f32_e32 v92, v92
	s_nop 0
	v_mul_f32_e32 v146, v75, v92
	v_cvt_pk_bf16_f32 v92, v146, s0
	v_add_u32_e32 v75, v102, v132
	ds_write_b16 v75, v92
	v_or_b32_e32 v92, 1, v81
	v_mad_u64_u32 v[92:93], s[22:23], v92, s73, v[70:71]
	v_add_u32_e32 v93, s2, v93
	v_lshl_add_u64 v[92:93], v[92:93], 0, s[4:5]
	v_lshl_add_u64 v[94:95], v[92:93], 0, v[72:73]
	global_load_ushort v94, v[94:95], off
	s_waitcnt vmcnt(0)
; __device__ __forceinline__ unsigned f2bf(float f) { return pk2(f, f) & 0xffffu; }
; __device__ __forceinline__ float sigmoidf_(float v) { return __builtin_amdgcn_rcpf(1.0f + __builtin_amdgcn_exp2f(v * -1.4426950408889634f)); }
; template <bool FINAL> __device__ __forceinline__ void lru_unit(const Args& a, unsigned char* ws, int l, int unit, const LruW& W, LAS unsigned char* lds, int tid_in) {
;     ...
;         for (int mt = 0; mt < 4; ++mt) {
;             float As = av[mt][0], Hs = bv[mt][0];
; #pragma unroll
;             for (int r = 1; r < 4; ++r) { Hs = av[mt][r] * Hs + bv[mt][r]; As *= av[mt][r]; }
;             float Ai = As, Hi = Hs;
;             { const float Ap = __shfl_up(Ai, 16), Hp = __shfl_up(Hi, 16); if (g >= 1) { Hi = Ai * Hp + Hi; Ai = Ai * Ap; } }
;             { const float Ap = __shfl_up(Ai, 32), Hp = __shfl_up(Hi, 32); if (g >= 2) { Hi = Ai * Hp + Hi; Ai = Ai * Ap; } }
;             float Ae = __shfl_up(Ai, 16), He = __shfl_up(Hi, 16); if (g == 0) { Ae = 1.f; He = 0.f; }
;             const float At = __shfl(Ai, fr + 48), Ht = __shfl(Hi, fr + 48);
;             if (FINAL) { float hc = Ae * carry + He;
; #pragma unroll
;                 for (int r = 0; r < 4; ++r) { hc = av[mt][r] * hc + bv[mt][r]; const float gt = bf2f(proj[(row0 + 16 * mt + 4 * g + r) * NPROJ + PC_DG + c]); const float u2 = 1.5957691216057308f * (gt + 0.044715f * gt * gt * gt); const float o = hc * gt * sigmoidf_(u2);
;                     Hrm[(16 * mt + 4 * g + r) * LR_RS + c] = (bf16)f2bf(o); ssp[mt][r] += o * o; } }
	v_lshlrev_b32_e32 v94, 16, v94
	v_mul_f32_e32 v95, 0x3d372713, v94
	v_mul_f32_e32 v95, v95, v94
	v_fma_f32 v95, v95, v94, v94
	v_mul_f32_e32 v95, 0x3fcc422a, v95
	v_mul_f32_e32 v95, 0xbfb8aa3b, v95
	v_exp_f32_e32 v95, v95
	v_mul_f32_e32 v94, v98, v94
	v_add_f32_e32 v95, 1.0, v95
	v_rcp_f32_e32 v95, v95
	s_nop 0
	v_mul_f32_e32 v138, v94, v95
	v_cvt_pk_bf16_f32 v94, v138, s0
	ds_write_b16 v75, v94 offset:1040
	v_or_b32_e32 v94, 2, v81
	v_mad_u64_u32 v[94:95], s[22:23], v94, s73, v[70:71]
	v_add_u32_e32 v95, s2, v95
	v_lshl_add_u64 v[94:95], v[94:95], 0, s[4:5]
	v_lshl_add_u64 v[98:99], v[94:95], 0, v[72:73]
	global_load_ushort v97, v[98:99], off
	s_waitcnt vmcnt(0)
	v_lshlrev_b32_e32 v97, 16, v97
	v_mul_f32_e32 v98, 0x3d372713, v97
	v_mul_f32_e32 v98, v98, v97
	v_fma_f32 v98, v98, v97, v97
	v_mul_f32_e32 v98, 0x3fcc422a, v98
	v_mul_f32_e32 v98, 0xbfb8aa3b, v98
	v_exp_f32_e32 v98, v98
	v_mul_f32_e32 v97, v103, v97
	v_add_f32_e32 v98, 1.0, v98
	v_rcp_f32_e32 v98, v98
	s_nop 0
	v_mul_f32_e32 v139, v97, v98
	v_cvt_pk_bf16_f32 v97, v139, s0
	ds_write_b16 v75, v97 offset:2080
	v_or_b32_e32 v97, 3, v81
	v_mad_u64_u32 v[98:99], s[22:23], v97, s73, v[70:71]
	v_add_u32_e32 v99, s2, v99
	v_lshl_add_u64 v[98:99], v[98:99], 0, s[4:5]
	v_lshl_add_u64 v[128:129], v[98:99], 0, v[72:73]
	global_load_ushort v97, v[128:129], off
	s_waitcnt vmcnt(0)
	v_lshlrev_b32_e32 v97, 16, v97
	v_mul_f32_e32 v103, 0x3d372713, v97
	v_mul_f32_e32 v103, v103, v97
	v_fma_f32 v103, v103, v97, v97
	v_mul_f32_e32 v103, 0x3fcc422a, v103
	v_mul_f32_e32 v103, 0xbfb8aa3b, v103
	v_exp_f32_e32 v103, v103
	v_mul_f32_e32 v97, v113, v97
	v_add_f32_e32 v103, 1.0, v103
	v_rcp_f32_e32 v103, v103
	s_nop 0
	v_mul_f32_e32 v142, v97, v103
	v_cvt_pk_bf16_f32 v97, v142, s0
	ds_write_b16 v75, v97 offset:3120
	v_fma_f32 v97, v115, v125, v111
	v_fma_f32 v97, v104, v97, v107
	v_fma_f32 v97, v106, v97, v77
	ds_bpermute_b32 v103, v136, v101
	ds_bpermute_b32 v105, v136, v97
	s_waitcnt lgkmcnt(1)
	v_mul_f32_e32 v103, v101, v103
	s_waitcnt lgkmcnt(0)
	v_fma_f32 v105, v101, v105, v97
	v_cndmask_b32_e32 v101, v103, v101, vcc
	v_cndmask_b32_e32 v97, v105, v97, vcc
	ds_bpermute_b32 v103, v137, v101
	ds_bpermute_b32 v105, v137, v97
	s_waitcnt lgkmcnt(1)
	v_mul_f32_e32 v103, v101, v103
	s_waitcnt lgkmcnt(0)
	v_fma_f32 v105, v101, v105, v97
	v_cndmask_b32_e64 v101, v101, v103, s[36:37]
	v_cndmask_b32_e64 v97, v97, v105, s[36:37]
	ds_bpermute_b32 v103, v136, v101
	ds_bpermute_b32 v105, v136, v97
	ds_bpermute_b32 v124, v169, v97 offset:192
	v_or_b32_e32 v97, s44, v100
	ds_bpermute_b32 v113, v169, v101 offset:192
	v_mad_u64_u32 v[100:101], s[22:23], v97, s73, v[70:71]
	s_waitcnt lgkmcnt(3)
	v_cndmask_b32_e64 v103, v103, 1.0, vcc
	s_waitcnt lgkmcnt(2)
	v_cndmask_b32_e64 v105, v105, 0, vcc
	v_add_u32_e32 v101, s2, v101
	v_fmac_f32_e32 v105, v109, v103
	v_lshl_add_u64 v[100:101], v[100:101], 0, s[4:5]
	v_fmac_f32_e32 v125, v127, v105
	v_lshl_add_u64 v[126:127], v[100:101], 0, v[72:73]
	global_load_ushort v97, v[126:127], off
	v_fmac_f32_e32 v111, v115, v125
	v_fmac_f32_e32 v107, v104, v111
	v_or_b32_e32 v104, 18, v81
	v_fmac_f32_e32 v77, v106, v107
	v_or_b32_e32 v106, 19, v81
	s_waitcnt lgkmcnt(0)
	v_fmac_f32_e32 v124, v109, v113
	v_mul_f32_e32 v109, v108, v110
	v_mul_f32_e32 v109, v112, v109
	v_mul_f32_e32 v109, v89, v109
	s_waitcnt vmcnt(0)
	v_lshlrev_b32_e32 v97, 16, v97
	v_mul_f32_e32 v103, 0x3d372713, v97
	v_mul_f32_e32 v103, v103, v97
	v_fma_f32 v103, v103, v97, v97
	v_mul_f32_e32 v103, 0x3fcc422a, v103
	v_mul_f32_e32 v103, 0xbfb8aa3b, v103
	v_exp_f32_e32 v103, v103
	v_mul_f32_e32 v97, v125, v97
	v_add_f32_e32 v103, 1.0, v103
	v_rcp_f32_e32 v103, v103
	s_nop 0
	v_mul_f32_e32 v143, v97, v103
	v_cvt_pk_bf16_f32 v103, v143, s0
	v_add_u32_e32 v97, v102, v133
	v_or_b32_e32 v102, 17, v81
	ds_write_b16 v97, v103
	v_mad_u64_u32 v[102:103], s[22:23], v102, s73, v[70:71]
	v_add_u32_e32 v103, s2, v103
	v_lshl_add_u64 v[102:103], v[102:103], 0, s[4:5]
	v_lshl_add_u64 v[114:115], v[102:103], 0, v[72:73]
	global_load_ushort v105, v[114:115], off
	s_waitcnt vmcnt(0)
	v_lshlrev_b32_e32 v105, 16, v105
	v_mul_f32_e32 v114, 0x3d372713, v105
	v_mul_f32_e32 v114, v114, v105
	v_fma_f32 v114, v114, v105, v105
	v_mul_f32_e32 v114, 0x3fcc422a, v114
	v_mul_f32_e32 v114, 0xbfb8aa3b, v114
	v_exp_f32_e32 v114, v114
	v_mul_f32_e32 v105, v111, v105
	v_add_f32_e32 v114, 1.0, v114
	v_rcp_f32_e32 v114, v114
	s_nop 0
	v_mul_f32_e32 v144, v105, v114
	v_cvt_pk_bf16_f32 v105, v144, s0
	ds_write_b16 v75, v105 offset:17680
	v_mad_u64_u32 v[104:105], s[22:23], v104, s73, v[70:71]
	v_add_u32_e32 v105, s2, v105
	v_lshl_add_u64 v[104:105], v[104:105], 0, s[4:5]
	v_lshl_add_u64 v[114:115], v[104:105], 0, v[72:73]
	global_load_ushort v111, v[114:115], off
	s_waitcnt vmcnt(0)
	v_lshlrev_b32_e32 v111, 16, v111
	v_mul_f32_e32 v114, 0x3d372713, v111
	v_mul_f32_e32 v114, v114, v111
	v_fma_f32 v114, v114, v111, v111
	v_mul_f32_e32 v114, 0x3fcc422a, v114
	v_mul_f32_e32 v114, 0xbfb8aa3b, v114
	v_exp_f32_e32 v114, v114
	v_mul_f32_e32 v111, v107, v111
	v_mad_u64_u32 v[106:107], s[22:23], v106, s73, v[70:71]
	v_add_f32_e32 v114, 1.0, v114
	v_rcp_f32_e32 v114, v114
	v_add_u32_e32 v107, s2, v107
	v_lshl_add_u64 v[106:107], v[106:107], 0, s[4:5]
	v_mul_f32_e32 v145, v111, v114
	v_cvt_pk_bf16_f32 v111, v145, s0
	v_lshl_add_u64 v[114:115], v[106:107], 0, v[72:73]
	ds_write_b16 v75, v111 offset:18720
	global_load_ushort v111, v[114:115], off
	s_waitcnt vmcnt(0)
; __device__ __forceinline__ unsigned f2bf(float f) { return pk2(f, f) & 0xffffu; }
; __device__ __forceinline__ float sigmoidf_(float v) { return __builtin_amdgcn_rcpf(1.0f + __builtin_amdgcn_exp2f(v * -1.4426950408889634f)); }
; template <bool FINAL> __device__ __forceinline__ void lru_unit(const Args& a, unsigned char* ws, int l, int unit, const LruW& W, LAS unsigned char* lds, int tid_in) {
;     ...
;         for (int mt = 0; mt < 4; ++mt) {
;             float As = av[mt][0], Hs = bv[mt][0];
; #pragma unroll
;             for (int r = 1; r < 4; ++r) { Hs = av[mt][r] * Hs + bv[mt][r]; As *= av[mt][r]; }
;             float Ai = As, Hi = Hs;
;             { const float Ap = __shfl_up(Ai, 16), Hp = __shfl_up(Hi, 16); if (g >= 1) { Hi = Ai * Hp + Hi; Ai = Ai * Ap; } }
;             { const float Ap = __shfl_up(Ai, 32), Hp = __shfl_up(Hi, 32); if (g >= 2) { Hi = Ai * Hp + Hi; Ai = Ai * Ap; } }
;             float Ae = __shfl_up(Ai, 16), He = __shfl_up(Hi, 16); if (g == 0) { Ae = 1.f; He = 0.f; }
;             const float At = __shfl(Ai, fr + 48), Ht = __shfl(Hi, fr + 48);
;             if (FINAL) { float hc = Ae * carry + He;
; #pragma unroll
;                 for (int r = 0; r < 4; ++r) { hc = av[mt][r] * hc + bv[mt][r]; const float gt = bf2f(proj[(row0 + 16 * mt + 4 * g + r) * NPROJ + PC_DG + c]); const float u2 = 1.5957691216057308f * (gt + 0.044715f * gt * gt * gt); const float o = hc * gt * sigmoidf_(u2);
;                     Hrm[(16 * mt + 4 * g + r) * LR_RS + c] = (bf16)f2bf(o); ssp[mt][r] += o * o; } }
;             carry = At * carry + Ht; atot *= At;
	v_lshlrev_b32_e32 v111, 16, v111
	v_mul_f32_e32 v114, 0x3d372713, v111
	v_mul_f32_e32 v114, v114, v111
	v_fma_f32 v114, v114, v111, v111
	v_mul_f32_e32 v114, 0x3fcc422a, v114
	v_mul_f32_e32 v77, v77, v111
	v_mul_f32_e32 v111, 0xbfb8aa3b, v114
	v_exp_f32_e32 v111, v111
	s_nop 0
	v_add_f32_e32 v111, 1.0, v111
	v_rcp_f32_e32 v111, v111
	s_nop 0
	v_mul_f32_e32 v147, v77, v111
	v_cvt_pk_bf16_f32 v77, v147, s0
	ds_write_b16 v75, v77 offset:19760
	v_fma_f32 v77, v110, v78, v79
	v_fma_f32 v77, v112, v77, v80
	v_fma_f32 v77, v89, v77, v88
	ds_bpermute_b32 v111, v136, v109
	ds_bpermute_b32 v113, v136, v77
	s_waitcnt lgkmcnt(1)
	v_mul_f32_e32 v111, v109, v111
	s_waitcnt lgkmcnt(0)
	v_fma_f32 v113, v109, v113, v77
	v_cndmask_b32_e32 v109, v111, v109, vcc
	v_cndmask_b32_e32 v77, v113, v77, vcc
	ds_bpermute_b32 v111, v137, v109
	ds_bpermute_b32 v113, v137, v77
	s_waitcnt lgkmcnt(1)
	v_mul_f32_e32 v111, v109, v111
	s_waitcnt lgkmcnt(0)
	v_fma_f32 v113, v109, v113, v77
	v_cndmask_b32_e64 v109, v109, v111, s[36:37]
	v_cndmask_b32_e64 v77, v77, v113, s[36:37]
	ds_bpermute_b32 v111, v136, v109
	ds_bpermute_b32 v113, v136, v77
	ds_bpermute_b32 v125, v169, v109 offset:192
	ds_bpermute_b32 v77, v169, v77 offset:192
	s_waitcnt lgkmcnt(3)
	v_cndmask_b32_e64 v111, v111, 1.0, vcc
	s_waitcnt lgkmcnt(2)
	v_cndmask_b32_e64 v113, v113, 0, vcc
	v_fmac_f32_e32 v113, v124, v111
	v_fmac_f32_e32 v78, v108, v113
	v_or_b32_e32 v108, 32, v81
	v_mad_u64_u32 v[108:109], s[22:23], v108, s73, v[70:71]
	v_add_u32_e32 v109, s2, v109
	v_lshl_add_u64 v[108:109], v[108:109], 0, s[4:5]
	v_lshl_add_u64 v[114:115], v[108:109], 0, v[72:73]
	global_load_ushort v111, v[114:115], off
	v_fmac_f32_e32 v79, v110, v78
	v_fmac_f32_e32 v80, v112, v79
	v_fmac_f32_e32 v88, v89, v80
	s_waitcnt lgkmcnt(0)
	v_fmac_f32_e32 v77, v124, v125
	s_waitcnt vmcnt(0)
	v_lshlrev_b32_e32 v111, 16, v111
	v_mul_f32_e32 v113, 0x3d372713, v111
	v_mul_f32_e32 v113, v113, v111
	v_fma_f32 v113, v113, v111, v111
	v_mul_f32_e32 v113, 0x3fcc422a, v113
	v_mul_f32_e32 v113, 0xbfb8aa3b, v113
	v_exp_f32_e32 v113, v113
	v_mul_f32_e32 v111, v78, v111
	v_or_b32_e32 v78, 33, v81
	v_add_f32_e32 v113, 1.0, v113
	v_rcp_f32_e32 v113, v113
	s_nop 0
	v_mul_f32_e32 v148, v111, v113
	v_cvt_pk_bf16_f32 v111, v148, s0
	ds_write_b16 v97, v111 offset:16640
	v_mad_u64_u32 v[110:111], s[22:23], v78, s73, v[70:71]
	v_add_u32_e32 v111, s2, v111
	v_lshl_add_u64 v[110:111], v[110:111], 0, s[4:5]
	v_lshl_add_u64 v[114:115], v[110:111], 0, v[72:73]
	global_load_ushort v78, v[114:115], off
	s_waitcnt vmcnt(0)
	v_lshlrev_b32_e32 v78, 16, v78
	v_mul_f32_e32 v113, 0x3d372713, v78
	v_mul_f32_e32 v113, v113, v78
	v_fma_f32 v113, v113, v78, v78
	v_mul_f32_e32 v113, 0x3fcc422a, v113
	v_mul_f32_e32 v113, 0xbfb8aa3b, v113
	v_exp_f32_e32 v113, v113
	v_mul_f32_e32 v78, v79, v78
	v_add_f32_e32 v113, 1.0, v113
	v_rcp_f32_e32 v113, v113
	s_nop 0
	v_mul_f32_e32 v149, v78, v113
	v_cvt_pk_bf16_f32 v78, v149, s0
	ds_write_b16 v75, v78 offset:34320
	v_or_b32_e32 v78, 34, v81
	v_mad_u64_u32 v[78:79], s[22:23], v78, s73, v[70:71]
	v_add_u32_e32 v79, s2, v79
	v_lshl_add_u64 v[112:113], v[78:79], 0, s[4:5]
	v_lshl_add_u64 v[78:79], v[112:113], 0, v[72:73]
	global_load_ushort v78, v[78:79], off
	s_waitcnt vmcnt(0)
	v_lshlrev_b32_e32 v78, 16, v78
	v_mul_f32_e32 v79, 0x3d372713, v78
	v_mul_f32_e32 v79, v79, v78
	v_fma_f32 v79, v79, v78, v78
	v_mul_f32_e32 v79, 0x3fcc422a, v79
	v_mul_f32_e32 v79, 0xbfb8aa3b, v79
	v_exp_f32_e32 v79, v79
	v_mul_f32_e32 v78, v80, v78
	v_add_f32_e32 v79, 1.0, v79
	v_rcp_f32_e32 v79, v79
	s_nop 0
	v_mul_f32_e32 v151, v78, v79
	v_cvt_pk_bf16_f32 v78, v151, s0
	ds_write_b16 v75, v78 offset:35360
	v_or_b32_e32 v78, 35, v81
	v_mad_u64_u32 v[78:79], s[22:23], v78, s73, v[70:71]
	v_add_u32_e32 v79, s2, v79
	v_lshl_add_u64 v[114:115], v[78:79], 0, s[4:5]
	v_lshl_add_u64 v[78:79], v[114:115], 0, v[72:73]
	global_load_ushort v78, v[78:79], off
	s_waitcnt vmcnt(0)
	v_lshlrev_b32_e32 v78, 16, v78
	v_mul_f32_e32 v79, 0x3d372713, v78
	v_mul_f32_e32 v79, v79, v78
	v_fma_f32 v79, v79, v78, v78
	v_mul_f32_e32 v79, 0x3fcc422a, v79
	v_mul_f32_e32 v79, 0xbfb8aa3b, v79
	v_exp_f32_e32 v79, v79
	v_mul_f32_e32 v78, v88, v78
	v_add_f32_e32 v79, 1.0, v79
	v_rcp_f32_e32 v79, v79
	s_nop 0
	v_mul_f32_e32 v152, v78, v79
	v_cvt_pk_bf16_f32 v78, v152, s0
	ds_write_b16 v75, v78 offset:36400
	v_fma_f32 v78, v85, v82, v83
	v_mul_f32_e32 v79, v87, v85
	v_fma_f32 v78, v86, v78, v84
	v_mul_f32_e32 v79, v86, v79
	v_fma_f32 v78, v76, v78, v74
	v_mul_f32_e32 v79, v76, v79
	ds_bpermute_b32 v80, v136, v79
	ds_bpermute_b32 v88, v136, v78
	s_waitcnt lgkmcnt(1)
	v_mul_f32_e32 v80, v79, v80
	s_waitcnt lgkmcnt(0)
	v_fma_f32 v88, v79, v88, v78
	v_cndmask_b32_e32 v79, v80, v79, vcc
	v_cndmask_b32_e32 v78, v88, v78, vcc
	ds_bpermute_b32 v80, v137, v79
	ds_bpermute_b32 v88, v137, v78
	s_waitcnt lgkmcnt(1)
	v_mul_f32_e32 v80, v79, v80
	s_waitcnt lgkmcnt(0)
	v_fma_f32 v88, v79, v88, v78
	v_cndmask_b32_e64 v79, v79, v80, s[36:37]
	v_cndmask_b32_e64 v78, v78, v88, s[36:37]
	ds_bpermute_b32 v79, v136, v79
	ds_bpermute_b32 v78, v136, v78
	s_waitcnt lgkmcnt(1)
	v_cndmask_b32_e64 v79, v79, 1.0, vcc
	s_waitcnt lgkmcnt(0)
	v_cndmask_b32_e64 v78, v78, 0, vcc
	v_fmac_f32_e32 v78, v77, v79
	v_or_b32_e32 v77, 48, v81
	v_fmac_f32_e32 v82, v87, v78
	v_mad_u64_u32 v[78:79], s[22:23], v77, s73, v[70:71]
	v_add_u32_e32 v79, s2, v79
	v_lshl_add_u64 v[124:125], v[78:79], 0, s[4:5]
	v_lshl_add_u64 v[78:79], v[124:125], 0, v[72:73]
	global_load_ushort v77, v[78:79], off
	v_fmac_f32_e32 v83, v85, v82
	v_fmac_f32_e32 v84, v86, v83
	v_fmac_f32_e32 v74, v76, v84
	v_or_b32_e32 v76, 51, v81
	s_waitcnt vmcnt(0)
; __device__ __forceinline__ unsigned f2bf(float f) { return pk2(f, f) & 0xffffu; }
; __device__ __forceinline__ float sigmoidf_(float v) { return __builtin_amdgcn_rcpf(1.0f + __builtin_amdgcn_exp2f(v * -1.4426950408889634f)); }
; __device__ __forceinline__ float softplusf_(float v) { return v > 20.f ? v : log1pf(__expf(v)); }
; template <bool FINAL> __device__ __forceinline__ void lru_unit(const Args& a, unsigned char* ws, int l, int unit, const LruW& W, LAS unsigned char* lds, int tid_in) {
;     ...
;         const float ba = a.in[I_LBA][l * 512 + c], bx = a.in[I_LBX][l * 512 + c], spn = softplusf_(-a.in[I_LAP][l * 512 + c]);
;         float av[4][4], bv[4][4]; const float carry0 = FINAL ? LRC[((size_t)b * 256 + chunk) * 512 + c] : 0.f;
;     ...
;             if (FINAL) { float hc = Ae * carry + He;
; #pragma unroll
;                 for (int r = 0; r < 4; ++r) { hc = av[mt][r] * hc + bv[mt][r]; const float gt = bf2f(proj[(row0 + 16 * mt + 4 * g + r) * NPROJ + PC_DG + c]); const float u2 = 1.5957691216057308f * (gt + 0.044715f * gt * gt * gt); const float o = hc * gt * sigmoidf_(u2);
;                     Hrm[(16 * mt + 4 * g + r) * LR_RS + c] = (bf16)f2bf(o); ssp[mt][r] += o * o; } }
;             carry = At * carry + Ht; atot *= At;
	v_lshlrev_b32_e32 v77, 16, v77
	v_mul_f32_e32 v78, 0x3d372713, v77
	v_mul_f32_e32 v78, v78, v77
	v_fma_f32 v78, v78, v77, v77
	v_mul_f32_e32 v78, 0x3fcc422a, v78
	v_mul_f32_e32 v78, 0xbfb8aa3b, v78
	v_exp_f32_e32 v78, v78
	v_mul_f32_e32 v77, v82, v77
	v_add_f32_e32 v78, 1.0, v78
	v_rcp_f32_e32 v78, v78
	s_nop 0
	v_mul_f32_e32 v153, v77, v78
	v_cvt_pk_bf16_f32 v77, v153, s0
	ds_write_b16 v97, v77 offset:33280
	v_or_b32_e32 v77, 49, v81
	v_mad_u64_u32 v[78:79], s[22:23], v77, s73, v[70:71]
	v_add_u32_e32 v79, s2, v79
	v_lshl_add_u64 v[126:127], v[78:79], 0, s[4:5]
	v_lshl_add_u64 v[78:79], v[126:127], 0, v[72:73]
	global_load_ushort v77, v[78:79], off
	s_waitcnt vmcnt(0)
	v_lshlrev_b32_e32 v77, 16, v77
	v_mul_f32_e32 v78, 0x3d372713, v77
	v_mul_f32_e32 v78, v78, v77
	v_fma_f32 v78, v78, v77, v77
	v_mul_f32_e32 v78, 0x3fcc422a, v78
	v_mul_f32_e32 v78, 0xbfb8aa3b, v78
	v_exp_f32_e32 v78, v78
	v_mul_f32_e32 v77, v83, v77
	v_add_f32_e32 v78, 1.0, v78
	v_rcp_f32_e32 v78, v78
	s_nop 0
	v_mul_f32_e32 v154, v77, v78
	v_cvt_pk_bf16_f32 v77, v154, s0
	ds_write_b16 v75, v77 offset:50960
	v_or_b32_e32 v77, 50, v81
	v_mad_u64_u32 v[78:79], s[22:23], v77, s73, v[70:71]
	v_mad_u64_u32 v[70:71], s[22:23], v76, s73, v[70:71]
	v_add_u32_e32 v79, s2, v79
	v_add_u32_e32 v71, s2, v71
	v_lshl_add_u64 v[128:129], v[78:79], 0, s[4:5]
	v_lshl_add_u64 v[130:131], v[70:71], 0, s[4:5]
	v_lshl_add_u64 v[78:79], v[128:129], 0, v[72:73]
	v_lshl_add_u64 v[70:71], v[130:131], 0, v[72:73]
	global_load_ushort v77, v[78:79], off
	s_mov_b32 s2, 0xc1a00000
	global_load_ushort v70, v[70:71], off
	s_waitcnt vmcnt(1)
	v_lshlrev_b32_e32 v77, 16, v77
	v_mul_f32_e32 v78, 0x3d372713, v77
	s_waitcnt vmcnt(0)
	v_lshlrev_b32_e32 v70, 16, v70
	v_mul_f32_e32 v71, 0x3d372713, v70
	v_mul_f32_e32 v78, v78, v77
	v_mul_f32_e32 v71, v71, v70
	v_fma_f32 v78, v78, v77, v77
	v_fma_f32 v71, v71, v70, v70
	v_mul_f32_e32 v78, 0x3fcc422a, v78
	v_mul_f32_e32 v71, 0x3fcc422a, v71
	v_mul_f32_e32 v78, 0xbfb8aa3b, v78
	v_mul_f32_e32 v71, 0xbfb8aa3b, v71
	v_exp_f32_e32 v78, v78
	v_exp_f32_e32 v71, v71
	v_mul_f32_e32 v77, v84, v77
	v_mul_f32_e32 v70, v74, v70
	v_add_f32_e32 v78, 1.0, v78
	v_add_f32_e32 v71, 1.0, v71
	v_rcp_f32_e32 v78, v78
	v_rcp_f32_e32 v71, v71
	v_mul_f32_e32 v155, v77, v78
	v_mul_f32_e32 v158, v70, v71
	v_cvt_pk_bf16_f32 v77, v155, s0
	v_cvt_pk_bf16_f32 v70, v158, s0
	ds_write_b16 v75, v77 offset:52000
	ds_write_b16 v75, v70 offset:53040
	global_load_dword v177, v[116:117], off offset:64
	global_load_dword v170, v[118:119], off offset:64
	global_load_dword v70, v[120:121], off offset:64
	s_waitcnt vmcnt(0)
	v_xor_b32_e32 v181, 0x80000000, v70
	v_cmp_ngt_f32_e64 s[38:39], s2, v70
	s_and_saveexec_b64 s[22:23], s[38:39]
	s_cbranch_execz .LBB0_1372
; __device__ __forceinline__ float softplusf_(float v) { return v > 20.f ? v : log1pf(__expf(v)); }
; template <bool FINAL> __device__ __forceinline__ void lru_unit(const Args& a, unsigned char* ws, int l, int unit, const LruW& W, LAS unsigned char* lds, int tid_in) {
;     ...
;         const float ba = a.in[I_LBA][l * 512 + c], bx = a.in[I_LBX][l * 512 + c], spn = softplusf_(-a.in[I_LAP][l * 512 + c]);
	v_mul_f32_e32 v70, 0xbfb8aa3b, v70
	v_exp_f32_e32 v84, v70
	s_mov_b32 s2, 0x3f2aaaab
	v_add_f32_e32 v72, 1.0, v84
	v_frexp_mant_f32_e32 v74, v72
	v_cvt_f64_f32_e32 v[70:71], v72
	v_frexp_exp_i32_f64_e32 v70, v[70:71]
	v_cmp_gt_f32_e64 s[38:39], s2, v74
	v_add_f32_e32 v73, -1.0, v72
	v_sub_f32_e32 v75, v73, v72
	v_subbrev_co_u32_e64 v78, s[38:39], 0, v70, s[38:39]
	v_sub_u32_e32 v70, 0, v78
	v_sub_f32_e32 v73, v84, v73
	v_add_f32_e32 v75, 1.0, v75
	v_ldexp_f32 v71, v72, v70
	v_add_f32_e32 v73, v73, v75
	v_add_f32_e32 v72, -1.0, v71
	v_add_f32_e32 v74, 1.0, v71
	v_ldexp_f32 v70, v73, v70
	v_add_f32_e32 v73, 1.0, v72
	v_add_f32_e32 v75, -1.0, v74
	v_sub_f32_e32 v73, v71, v73
	v_sub_f32_e32 v71, v71, v75
	v_add_f32_e32 v73, v70, v73
	v_add_f32_e32 v70, v70, v71
	v_add_f32_e32 v79, v74, v70
	v_rcp_f32_e32 v81, v79
	v_sub_f32_e32 v71, v79, v74
	v_sub_f32_e32 v80, v70, v71
	v_add_f32_e32 v71, v72, v73
	v_mul_f32_e32 v83, v71, v81
	v_sub_f32_e32 v70, v71, v72
	v_mul_f32_e32 v72, v79, v83
	v_fma_f32 v74, v83, v79, -v72
	v_fmac_f32_e32 v74, v83, v80
	v_sub_f32_e32 v82, v73, v70
	v_add_f32_e32 v70, v72, v74
	v_sub_f32_e32 v73, v71, v70
	v_pk_add_f32 v[76:77], v[70:71], v[72:73] neg_lo:[0,1] neg_hi:[0,1]
	v_mov_b32_e32 v75, v70
	v_pk_add_f32 v[70:71], v[76:77], v[74:75] neg_lo:[0,1] neg_hi:[0,1]
	s_mov_b32 s2, 0x3f317218
	v_add_f32_e32 v71, v82, v71
	v_add_f32_e32 v70, v70, v71
	v_add_f32_e32 v71, v73, v70
	v_mul_f32_e32 v82, v81, v71
	v_mul_f32_e32 v72, v79, v82
	v_fma_f32 v74, v82, v79, -v72
	v_fmac_f32_e32 v74, v82, v80
	v_sub_f32_e32 v73, v73, v71
	v_add_f32_e32 v79, v70, v73
	v_add_f32_e32 v70, v72, v74
	v_sub_f32_e32 v73, v71, v70
	v_pk_add_f32 v[76:77], v[70:71], v[72:73] neg_lo:[0,1] neg_hi:[0,1]
	v_mov_b32_e32 v75, v70
	v_pk_add_f32 v[70:71], v[76:77], v[74:75] neg_lo:[0,1] neg_hi:[0,1]
	s_nop 0
	v_add_f32_e32 v71, v79, v71
	v_add_f32_e32 v70, v70, v71
	v_add_f32_e32 v71, v83, v82
	v_add_f32_e32 v70, v73, v70
	v_sub_f32_e32 v72, v71, v83
	v_mul_f32_e32 v70, v81, v70
	v_sub_f32_e32 v72, v82, v72
	v_add_f32_e32 v72, v72, v70
	v_add_f32_e32 v74, v71, v72
	v_mul_f32_e32 v75, v74, v74
	v_fmamk_f32 v70, v75, 0x3e9b6dac, v196
	v_fmaak_f32 v163, v75, v70, 0x3f2aaada
	v_cvt_f32_i32_e32 v70, v78
	v_sub_f32_e32 v71, v74, v71
	v_sub_f32_e32 v71, v72, v71
	v_ldexp_f32 v76, v71, 1
	v_mul_f32_e32 v71, v74, v75
	v_ldexp_f32 v73, v74, 1
	v_pk_mul_f32 v[74:75], v[70:71], v[162:163]
	s_nop 0
	v_fma_f32 v72, v70, s2, -v74
	v_fmac_f32_e32 v72, 0xb102e308, v70
	v_pk_add_f32 v[70:71], v[74:75], v[72:73]
	s_mov_b32 s2, 0x7f800000
	v_sub_f32_e32 v73, v71, v73
	v_sub_f32_e32 v73, v75, v73
	v_add_f32_e32 v77, v76, v73
	v_mov_b32_e32 v76, v74
	v_pk_add_f32 v[74:75], v[70:71], v[74:75] neg_lo:[0,1] neg_hi:[0,1]
	v_pk_add_f32 v[78:79], v[70:71], v[76:77]
	v_mov_b32_e32 v73, v70
	v_mov_b32_e32 v75, v79
	v_pk_add_f32 v[80:81], v[72:73], v[74:75] neg_lo:[0,1] neg_hi:[0,1]
	v_pk_add_f32 v[72:73], v[72:73], v[74:75]
	v_mov_b32_e32 v76, v77
	v_pk_add_f32 v[74:75], v[72:73], v[70:71] op_sel:[1,0] op_sel_hi:[0,1] neg_lo:[0,1] neg_hi:[0,1]
	v_pk_add_f32 v[82:83], v[78:79], v[74:75] op_sel_hi:[1,0] neg_lo:[0,1] neg_hi:[0,1]
	v_mov_b32_e32 v78, v79
	v_mov_b32_e32 v79, v73
	v_pk_mov_b32 v[74:75], v[70:71], v[74:75] op_sel:[1,0]
	v_mov_b32_e32 v77, v70
	v_pk_add_f32 v[74:75], v[78:79], v[74:75] neg_lo:[0,1] neg_hi:[0,1]
	v_mov_b32_e32 v82, v80
	v_pk_add_f32 v[70:71], v[76:77], v[74:75] neg_lo:[0,1] neg_hi:[0,1]
	v_mov_b32_e32 v81, v73
	v_pk_add_f32 v[74:75], v[82:83], v[70:71]
	v_cmp_neq_f32_e64 s[38:39], s2, v84
	v_pk_add_f32 v[76:77], v[74:75], v[74:75] op_sel:[0,1] op_sel_hi:[1,0]
	s_mov_b32 s2, 0x33800000
	v_pk_add_f32 v[72:73], v[72:73], v[76:77] op_sel:[1,0] op_sel_hi:[0,1]
	v_mov_b32_e32 v75, v72
	v_pk_add_f32 v[78:79], v[74:75], v[80:81] neg_lo:[0,1] neg_hi:[0,1]
	v_mov_b32_e32 v71, v76
	v_sub_f32_e32 v73, v74, v78
	v_pk_add_f32 v[70:71], v[70:71], v[78:79] neg_lo:[0,1] neg_hi:[0,1]
	v_sub_f32_e32 v73, v80, v73
	v_add_f32_e32 v70, v70, v73
	v_add_f32_e32 v70, v70, v71
	v_add_f32_e32 v70, v72, v70
	v_cndmask_b32_e64 v70, v200, v70, s[38:39]
	v_cmp_ngt_f32_e64 s[38:39], -1.0, v84
	s_nop 1
	v_cndmask_b32_e64 v70, v201, v70, s[38:39]
	v_cmp_neq_f32_e64 s[38:39], -1.0, v84
	s_nop 1
	v_cndmask_b32_e64 v70, v202, v70, s[38:39]
	v_cmp_lt_f32_e64 s[38:39], |v84|, s2
	s_nop 1
	v_cndmask_b32_e64 v181, v70, v84, s[38:39]
